# non-temporal hint on the P1 in-projection output (Z) stores and P5 activation stores
# speedup vs baseline: 1.0601x; 1.0082x over previous
.LBB0_218:
	s_lshl_b32 s1, s4, 8
	v_lshl_add_u32 v160, s0, 8, v139
	v_or_b32_e32 v136, s1, v153
	s_cmp_gt_i32 s4, 3
	s_mov_b64 s[2:3], -1
	s_cbranch_scc0 .LBB0_256
	s_cmp_gt_u32 s4, 13
	s_cbranch_scc0 .LBB0_221
	v_mul_f32_e32 v149, 0xbfb8aa3b, v124
	v_exp_f32_e32 v150, v149
	v_mul_f32_e32 v149, 0xbfb8aa3b, v120
	v_exp_f32_e32 v151, v149
	v_mul_f32_e32 v161, 0xbfb8aa3b, v125
	v_exp_f32_e32 v161, v161
	v_mul_f32_e32 v162, 0xbfb8aa3b, v121
	v_exp_f32_e32 v163, v162
	v_add_f32_e32 v151, 1.0, v151
	v_rcp_f32_e32 v164, v151
	v_add_f32_e32 v151, 1.0, v161
	v_mul_f32_e32 v161, 0xbfb8aa3b, v126
	v_rcp_f32_e32 v162, v151
	v_add_f32_e32 v151, 1.0, v163
	v_exp_f32_e32 v161, v161
	v_mul_f32_e32 v163, 0xbfb8aa3b, v122
	v_exp_f32_e32 v163, v163
	v_rcp_f32_e32 v166, v151
	v_add_f32_e32 v151, 1.0, v161
	v_mul_f32_e32 v161, 0xbfb8aa3b, v127
	v_rcp_f32_e32 v168, v151
	v_add_f32_e32 v151, 1.0, v163
	v_exp_f32_e32 v161, v161
	v_mul_f32_e32 v163, 0xbfb8aa3b, v123
	v_exp_f32_e32 v163, v163
	v_rcp_f32_e32 v170, v151
	v_add_f32_e32 v151, 1.0, v161
	v_rcp_f32_e32 v172, v151
	v_add_f32_e32 v151, 1.0, v163
	v_mul_f32_e32 v161, 0xbfb8aa3b, v116
	v_mul_f32_e32 v163, 0xbfb8aa3b, v112
	v_exp_f32_e32 v161, v161
	v_exp_f32_e32 v163, v163
	v_rcp_f32_e32 v174, v151
	v_mul_f32_e32 v165, 0xbfb8aa3b, v113
	v_add_f32_e32 v151, 1.0, v161
	v_add_f32_e32 v161, 1.0, v163
	v_mul_f32_e32 v163, 0xbfb8aa3b, v117
	v_exp_f32_e32 v163, v163
	v_exp_f32_e32 v167, v165
	v_rcp_f32_e32 v165, v161
	v_add_f32_e32 v150, 1.0, v150
	v_add_f32_e32 v161, 1.0, v163
	v_rcp_f32_e32 v163, v161
	v_add_f32_e32 v161, 1.0, v167
	v_mul_f32_e32 v167, 0xbfb8aa3b, v118
	v_exp_f32_e32 v169, v167
	v_mul_f32_e32 v167, 0xbfb8aa3b, v114
	v_exp_f32_e32 v171, v167
	v_rcp_f32_e32 v167, v161
	v_add_f32_e32 v161, 1.0, v169
	v_rcp_f32_e32 v169, v161
	v_add_f32_e32 v161, 1.0, v171
	v_mul_f32_e32 v171, 0xbfb8aa3b, v119
	v_exp_f32_e32 v173, v171
	v_mul_f32_e32 v171, 0xbfb8aa3b, v115
	v_rcp_f32_e32 v150, v150
	v_rcp_f32_e32 v151, v151
	v_exp_f32_e32 v175, v171
	v_rcp_f32_e32 v171, v161
	v_add_f32_e32 v161, 1.0, v173
	v_rcp_f32_e32 v173, v161
	v_add_f32_e32 v161, 1.0, v175
	v_pk_fma_f32 v[150:151], v[150:151], s[24:25], 0.5 op_sel_hi:[1,0,0]
	v_rcp_f32_e32 v175, v161
	v_cvt_u32_f32_e32 v161, v151
	v_cvt_u32_f32_e32 v176, v150
	v_pk_fma_f32 v[150:151], v[162:163], s[24:25], 0.5 op_sel_hi:[1,0,0]
	v_readlane_b32 s2, v246, 26
	v_cvt_u32_f32_e32 v162, v150
	v_cvt_u32_f32_e32 v163, v151
	v_pk_fma_f32 v[150:151], v[168:169], s[24:25], 0.5 op_sel_hi:[1,0,0]
	v_readlane_b32 s3, v246, 27
	v_cvt_u32_f32_sdwa v168, v150 dst_sel:WORD_1 dst_unused:UNUSED_PAD src0_sel:DWORD
	v_cvt_u32_f32_sdwa v169, v151 dst_sel:WORD_1 dst_unused:UNUSED_PAD src0_sel:DWORD
	v_pk_fma_f32 v[150:151], v[172:173], s[24:25], 0.5 op_sel_hi:[1,0,0]
	v_lshlrev_b32_e32 v163, 8, v163
	v_cvt_u32_f32_sdwa v150, v150 dst_sel:BYTE_3 dst_unused:UNUSED_PAD src0_sel:DWORD
	v_cvt_u32_f32_sdwa v151, v151 dst_sel:BYTE_3 dst_unused:UNUSED_PAD src0_sel:DWORD
	v_lshlrev_b32_e32 v162, 8, v162
	v_or_b32_e32 v161, v163, v161
	v_or_b32_e32 v162, v162, v176
	v_or_b32_e32 v161, v161, v169
	v_or_b32_e32 v162, v162, v168
	v_or_b32_e32 v163, v161, v151
	v_or_b32_e32 v162, v162, v150
	v_pk_fma_f32 v[150:151], v[164:165], s[24:25], 0.5 op_sel_hi:[1,0,0]
	v_add_u32_e32 v148, s1, v154
	v_cvt_u32_f32_e32 v161, v151
	v_cvt_u32_f32_e32 v164, v150
	v_pk_fma_f32 v[150:151], v[166:167], s[24:25], 0.5 op_sel_hi:[1,0,0]
	v_mov_b32_e32 v149, v137
	v_cvt_u32_f32_e32 v165, v150
	v_cvt_u32_f32_e32 v166, v151
	v_pk_fma_f32 v[150:151], v[170:171], s[24:25], 0.5 op_sel_hi:[1,0,0]
	v_lshlrev_b32_e32 v165, 8, v165
	v_cvt_u32_f32_sdwa v167, v150 dst_sel:WORD_1 dst_unused:UNUSED_PAD src0_sel:DWORD
	v_cvt_u32_f32_sdwa v168, v151 dst_sel:WORD_1 dst_unused:UNUSED_PAD src0_sel:DWORD
	v_pk_fma_f32 v[150:151], v[174:175], s[24:25], 0.5 op_sel_hi:[1,0,0]
	v_lshlrev_b32_e32 v166, 8, v166
	v_cvt_u32_f32_sdwa v150, v150 dst_sel:BYTE_3 dst_unused:UNUSED_PAD src0_sel:DWORD
	v_cvt_u32_f32_sdwa v151, v151 dst_sel:BYTE_3 dst_unused:UNUSED_PAD src0_sel:DWORD
	v_or_b32_e32 v161, v166, v161
	v_or_b32_e32 v164, v165, v164
	v_or_b32_e32 v161, v161, v168
	v_or_b32_e32 v164, v164, v167
	v_or_b32_e32 v165, v161, v151
	v_or_b32_e32 v164, v164, v150
	v_mov_b64_e32 v[150:151], s[2:3]
	v_mad_i64_i32 v[166:167], s[2:3], v160, s51, v[150:151]
	v_lshl_add_u64 v[166:167], v[166:167], 0, v[148:149]
	v_add_co_u32_e32 v166, vcc, s52, v166
	v_mul_f32_e32 v161, 0xbfb8aa3b, v108
	s_nop 0
	v_addc_co_u32_e32 v167, vcc, 0, v167, vcc
	v_exp_f32_e32 v161, v161
	v_mul_f32_e32 v168, 0xbfb8aa3b, v104
	v_exp_f32_e32 v168, v168
	global_store_dwordx4 v[166:167], v[162:165], off offset:3072 nt
	v_add_f32_e32 v161, 1.0, v161
	s_nop 0
	v_mul_f32_e32 v163, 0xbfb8aa3b, v109
	v_exp_f32_e32 v163, v163
	v_mul_f32_e32 v164, 0xbfb8aa3b, v105
	v_exp_f32_e32 v165, v164
	v_rcp_f32_e32 v162, v161
	v_add_f32_e32 v161, 1.0, v168
	v_rcp_f32_e32 v164, v161
	v_add_f32_e32 v161, 1.0, v163
	v_mul_f32_e32 v163, 0xbfb8aa3b, v110
	v_rcp_f32_e32 v166, v161
	v_add_f32_e32 v161, 1.0, v165
	v_exp_f32_e32 v163, v163
	v_mul_f32_e32 v165, 0xbfb8aa3b, v106
	v_exp_f32_e32 v165, v165
	v_rcp_f32_e32 v168, v161
	v_add_f32_e32 v161, 1.0, v163
	v_mul_f32_e32 v163, 0xbfb8aa3b, v111
	v_rcp_f32_e32 v170, v161
	v_add_f32_e32 v161, 1.0, v165
	v_exp_f32_e32 v163, v163
	v_mul_f32_e32 v165, 0xbfb8aa3b, v107
	v_exp_f32_e32 v165, v165
	v_rcp_f32_e32 v172, v161
	v_add_f32_e32 v161, 1.0, v163
	v_mul_f32_e32 v163, 0xbfb8aa3b, v100
	v_rcp_f32_e32 v174, v161
	v_add_f32_e32 v161, 1.0, v165
	v_exp_f32_e32 v163, v163
	v_mul_f32_e32 v165, 0xbfb8aa3b, v96
	v_exp_f32_e32 v165, v165
	v_rcp_f32_e32 v176, v161
	v_add_f32_e32 v161, 1.0, v163
	v_rcp_f32_e32 v163, v161
	v_add_f32_e32 v161, 1.0, v165
	v_mul_f32_e32 v165, 0xbfb8aa3b, v101
	v_exp_f32_e32 v167, v165
	v_mul_f32_e32 v165, 0xbfb8aa3b, v97
	v_exp_f32_e32 v169, v165
	v_rcp_f32_e32 v165, v161
	v_add_f32_e32 v161, 1.0, v167
	v_rcp_f32_e32 v167, v161
	v_add_f32_e32 v161, 1.0, v169
	v_mul_f32_e32 v169, 0xbfb8aa3b, v102
	v_exp_f32_e32 v171, v169
	v_mul_f32_e32 v169, 0xbfb8aa3b, v98
	v_exp_f32_e32 v173, v169
	v_rcp_f32_e32 v169, v161
	v_add_f32_e32 v161, 1.0, v171
	v_rcp_f32_e32 v171, v161
	v_add_f32_e32 v161, 1.0, v173
	v_mul_f32_e32 v173, 0xbfb8aa3b, v103
	v_exp_f32_e32 v175, v173
	v_mul_f32_e32 v173, 0xbfb8aa3b, v99
	v_exp_f32_e32 v177, v173
	v_rcp_f32_e32 v173, v161
	v_add_f32_e32 v161, 1.0, v175
	v_rcp_f32_e32 v175, v161
	v_pk_fma_f32 v[162:163], v[162:163], s[24:25], 0.5 op_sel_hi:[1,0,0]
	v_add_f32_e32 v161, 1.0, v177
	v_cvt_u32_f32_e32 v178, v163
	v_cvt_u32_f32_e32 v179, v162
	v_pk_fma_f32 v[162:163], v[166:167], s[24:25], 0.5 op_sel_hi:[1,0,0]
	v_rcp_f32_e32 v177, v161
	v_cvt_u32_f32_e32 v166, v162
	v_cvt_u32_f32_e32 v167, v163
	v_pk_fma_f32 v[162:163], v[170:171], s[24:25], 0.5 op_sel_hi:[1,0,0]
	v_pk_fma_f32 v[164:165], v[164:165], s[24:25], 0.5 op_sel_hi:[1,0,0]
	v_cvt_u32_f32_sdwa v170, v162 dst_sel:WORD_1 dst_unused:UNUSED_PAD src0_sel:DWORD
	v_cvt_u32_f32_sdwa v171, v163 dst_sel:WORD_1 dst_unused:UNUSED_PAD src0_sel:DWORD
	v_pk_fma_f32 v[162:163], v[174:175], s[24:25], 0.5 op_sel_hi:[1,0,0]
	v_lshlrev_b32_e32 v167, 8, v167
	v_cvt_u32_f32_sdwa v162, v162 dst_sel:BYTE_3 dst_unused:UNUSED_PAD src0_sel:DWORD
	v_cvt_u32_f32_sdwa v163, v163 dst_sel:BYTE_3 dst_unused:UNUSED_PAD src0_sel:DWORD
	v_lshlrev_b32_e32 v166, 8, v166
	v_or_b32_e32 v167, v167, v178
	v_or_b32_e32 v166, v166, v179
	v_or_b32_e32 v167, v167, v171
	v_or_b32_e32 v166, v166, v170
	v_or_b32_e32 v163, v167, v163
	v_or_b32_e32 v162, v166, v162
	v_cvt_u32_f32_e32 v166, v165
	v_cvt_u32_f32_e32 v167, v164
	v_pk_fma_f32 v[164:165], v[168:169], s[24:25], 0.5 op_sel_hi:[1,0,0]
	v_or_b32_e32 v161, 16, v160
	v_cvt_u32_f32_e32 v168, v164
	v_cvt_u32_f32_e32 v169, v165
	v_pk_fma_f32 v[164:165], v[172:173], s[24:25], 0.5 op_sel_hi:[1,0,0]
	v_lshlrev_b32_e32 v168, 8, v168
	v_cvt_u32_f32_sdwa v170, v164 dst_sel:WORD_1 dst_unused:UNUSED_PAD src0_sel:DWORD
	v_cvt_u32_f32_sdwa v171, v165 dst_sel:WORD_1 dst_unused:UNUSED_PAD src0_sel:DWORD
	v_pk_fma_f32 v[164:165], v[176:177], s[24:25], 0.5 op_sel_hi:[1,0,0]
	v_lshlrev_b32_e32 v169, 8, v169
	v_cvt_u32_f32_sdwa v164, v164 dst_sel:BYTE_3 dst_unused:UNUSED_PAD src0_sel:DWORD
	v_cvt_u32_f32_sdwa v165, v165 dst_sel:BYTE_3 dst_unused:UNUSED_PAD src0_sel:DWORD
	v_or_b32_e32 v166, v169, v166
	v_or_b32_e32 v167, v168, v167
	v_or_b32_e32 v166, v166, v171
	v_or_b32_e32 v167, v167, v170
	v_or_b32_e32 v165, v166, v165
	v_or_b32_e32 v164, v167, v164
	v_mad_i64_i32 v[166:167], s[2:3], v161, s51, v[150:151]
	v_lshl_add_u64 v[166:167], v[166:167], 0, v[148:149]
	v_add_co_u32_e32 v166, vcc, s52, v166
	v_mul_f32_e32 v161, 0xbfb8aa3b, v92
	s_nop 0
	v_addc_co_u32_e32 v167, vcc, 0, v167, vcc
	v_exp_f32_e32 v161, v161
	v_mul_f32_e32 v168, 0xbfb8aa3b, v88
	v_exp_f32_e32 v168, v168
	global_store_dwordx4 v[166:167], v[162:165], off offset:3072 nt
	v_add_f32_e32 v161, 1.0, v161
	s_nop 0
	v_mul_f32_e32 v163, 0xbfb8aa3b, v93
	v_exp_f32_e32 v163, v163
	v_mul_f32_e32 v164, 0xbfb8aa3b, v89
	v_exp_f32_e32 v165, v164
	v_rcp_f32_e32 v162, v161
	v_add_f32_e32 v161, 1.0, v168
	v_rcp_f32_e32 v164, v161
	v_add_f32_e32 v161, 1.0, v163
	v_mul_f32_e32 v163, 0xbfb8aa3b, v94
	v_rcp_f32_e32 v166, v161
	v_add_f32_e32 v161, 1.0, v165
	v_exp_f32_e32 v163, v163
	v_mul_f32_e32 v165, 0xbfb8aa3b, v90
	v_exp_f32_e32 v165, v165
	v_rcp_f32_e32 v168, v161
	v_add_f32_e32 v161, 1.0, v163
	v_mul_f32_e32 v163, 0xbfb8aa3b, v95
	v_rcp_f32_e32 v170, v161
	v_add_f32_e32 v161, 1.0, v165
	v_exp_f32_e32 v163, v163
	v_mul_f32_e32 v165, 0xbfb8aa3b, v91
	v_exp_f32_e32 v165, v165
	v_rcp_f32_e32 v172, v161
	v_add_f32_e32 v161, 1.0, v163
	v_mul_f32_e32 v163, 0xbfb8aa3b, v84
	v_rcp_f32_e32 v174, v161
	v_add_f32_e32 v161, 1.0, v165
	v_exp_f32_e32 v163, v163
	v_mul_f32_e32 v165, 0xbfb8aa3b, v80
	v_exp_f32_e32 v165, v165
	v_rcp_f32_e32 v176, v161
	v_add_f32_e32 v161, 1.0, v163
	v_rcp_f32_e32 v163, v161
	v_add_f32_e32 v161, 1.0, v165
	v_mul_f32_e32 v165, 0xbfb8aa3b, v85
	v_exp_f32_e32 v167, v165
	v_mul_f32_e32 v165, 0xbfb8aa3b, v81
	v_exp_f32_e32 v169, v165
	v_rcp_f32_e32 v165, v161
	v_add_f32_e32 v161, 1.0, v167
	v_rcp_f32_e32 v167, v161
	v_add_f32_e32 v161, 1.0, v169
	v_mul_f32_e32 v169, 0xbfb8aa3b, v86
	v_exp_f32_e32 v171, v169
	v_mul_f32_e32 v169, 0xbfb8aa3b, v82
	v_exp_f32_e32 v173, v169
	v_rcp_f32_e32 v169, v161
	v_add_f32_e32 v161, 1.0, v171
	v_rcp_f32_e32 v171, v161
	v_add_f32_e32 v161, 1.0, v173
	v_mul_f32_e32 v173, 0xbfb8aa3b, v87
	v_exp_f32_e32 v175, v173
	v_mul_f32_e32 v173, 0xbfb8aa3b, v83
	v_exp_f32_e32 v177, v173
	v_rcp_f32_e32 v173, v161
	v_add_f32_e32 v161, 1.0, v175
	v_rcp_f32_e32 v175, v161
	v_pk_fma_f32 v[162:163], v[162:163], s[24:25], 0.5 op_sel_hi:[1,0,0]
	v_add_f32_e32 v161, 1.0, v177
	v_cvt_u32_f32_e32 v178, v163
	v_cvt_u32_f32_e32 v179, v162
	v_pk_fma_f32 v[162:163], v[166:167], s[24:25], 0.5 op_sel_hi:[1,0,0]
	v_rcp_f32_e32 v177, v161
	v_cvt_u32_f32_e32 v166, v162
	v_cvt_u32_f32_e32 v167, v163
	v_pk_fma_f32 v[162:163], v[170:171], s[24:25], 0.5 op_sel_hi:[1,0,0]
	v_pk_fma_f32 v[164:165], v[164:165], s[24:25], 0.5 op_sel_hi:[1,0,0]
	v_cvt_u32_f32_sdwa v170, v162 dst_sel:WORD_1 dst_unused:UNUSED_PAD src0_sel:DWORD
	v_cvt_u32_f32_sdwa v171, v163 dst_sel:WORD_1 dst_unused:UNUSED_PAD src0_sel:DWORD
	v_pk_fma_f32 v[162:163], v[174:175], s[24:25], 0.5 op_sel_hi:[1,0,0]
	v_lshlrev_b32_e32 v167, 8, v167
	v_cvt_u32_f32_sdwa v162, v162 dst_sel:BYTE_3 dst_unused:UNUSED_PAD src0_sel:DWORD
	v_cvt_u32_f32_sdwa v163, v163 dst_sel:BYTE_3 dst_unused:UNUSED_PAD src0_sel:DWORD
	v_lshlrev_b32_e32 v166, 8, v166
	v_or_b32_e32 v167, v167, v178
	v_or_b32_e32 v166, v166, v179
	v_or_b32_e32 v167, v167, v171
	v_or_b32_e32 v166, v166, v170
	v_or_b32_e32 v163, v167, v163
	v_or_b32_e32 v162, v166, v162
	v_cvt_u32_f32_e32 v166, v165
	v_cvt_u32_f32_e32 v167, v164
	v_pk_fma_f32 v[164:165], v[168:169], s[24:25], 0.5 op_sel_hi:[1,0,0]
	v_or_b32_e32 v161, 32, v160
	v_cvt_u32_f32_e32 v168, v164
	v_cvt_u32_f32_e32 v169, v165
	v_pk_fma_f32 v[164:165], v[172:173], s[24:25], 0.5 op_sel_hi:[1,0,0]
	v_lshlrev_b32_e32 v168, 8, v168
	v_cvt_u32_f32_sdwa v170, v164 dst_sel:WORD_1 dst_unused:UNUSED_PAD src0_sel:DWORD
	v_cvt_u32_f32_sdwa v171, v165 dst_sel:WORD_1 dst_unused:UNUSED_PAD src0_sel:DWORD
	v_pk_fma_f32 v[164:165], v[176:177], s[24:25], 0.5 op_sel_hi:[1,0,0]
	v_lshlrev_b32_e32 v169, 8, v169
	v_cvt_u32_f32_sdwa v164, v164 dst_sel:BYTE_3 dst_unused:UNUSED_PAD src0_sel:DWORD
	v_cvt_u32_f32_sdwa v165, v165 dst_sel:BYTE_3 dst_unused:UNUSED_PAD src0_sel:DWORD
	v_or_b32_e32 v166, v169, v166
	v_or_b32_e32 v167, v168, v167
	v_or_b32_e32 v166, v166, v171
	v_or_b32_e32 v167, v167, v170
	v_or_b32_e32 v165, v166, v165
	v_or_b32_e32 v164, v167, v164
	v_mad_i64_i32 v[166:167], s[2:3], v161, s51, v[150:151]
	v_lshl_add_u64 v[166:167], v[166:167], 0, v[148:149]
	v_add_co_u32_e32 v166, vcc, s52, v166
	v_mul_f32_e32 v161, 0xbfb8aa3b, v76
	s_nop 0
	v_addc_co_u32_e32 v167, vcc, 0, v167, vcc
	v_exp_f32_e32 v161, v161
	v_mul_f32_e32 v168, 0xbfb8aa3b, v72
	v_exp_f32_e32 v168, v168
	global_store_dwordx4 v[166:167], v[162:165], off offset:3072 nt
	v_add_f32_e32 v161, 1.0, v161
	s_nop 0
	v_mul_f32_e32 v163, 0xbfb8aa3b, v77
	v_exp_f32_e32 v163, v163
	v_mul_f32_e32 v164, 0xbfb8aa3b, v73
	v_exp_f32_e32 v165, v164
	v_rcp_f32_e32 v162, v161
	v_add_f32_e32 v161, 1.0, v168
	v_rcp_f32_e32 v164, v161
	v_add_f32_e32 v161, 1.0, v163
	v_mul_f32_e32 v163, 0xbfb8aa3b, v78
	v_rcp_f32_e32 v166, v161
	v_add_f32_e32 v161, 1.0, v165
	v_exp_f32_e32 v163, v163
	v_mul_f32_e32 v165, 0xbfb8aa3b, v74
	v_exp_f32_e32 v165, v165
	v_rcp_f32_e32 v168, v161
	v_add_f32_e32 v161, 1.0, v163
	v_mul_f32_e32 v163, 0xbfb8aa3b, v79
	v_rcp_f32_e32 v170, v161
	v_add_f32_e32 v161, 1.0, v165
	v_exp_f32_e32 v163, v163
	v_mul_f32_e32 v165, 0xbfb8aa3b, v75
	v_exp_f32_e32 v165, v165
	v_rcp_f32_e32 v172, v161
	v_add_f32_e32 v161, 1.0, v163
	v_mul_f32_e32 v163, 0xbfb8aa3b, v68
	v_rcp_f32_e32 v174, v161
	v_add_f32_e32 v161, 1.0, v165
	v_exp_f32_e32 v163, v163
	v_mul_f32_e32 v165, 0xbfb8aa3b, v64
	v_exp_f32_e32 v165, v165
	v_rcp_f32_e32 v176, v161
	v_add_f32_e32 v161, 1.0, v163
	v_rcp_f32_e32 v163, v161
	v_add_f32_e32 v161, 1.0, v165
	v_mul_f32_e32 v165, 0xbfb8aa3b, v69
	v_exp_f32_e32 v167, v165
	v_mul_f32_e32 v165, 0xbfb8aa3b, v65
	v_exp_f32_e32 v169, v165
	v_rcp_f32_e32 v165, v161
	v_add_f32_e32 v161, 1.0, v167
	v_rcp_f32_e32 v167, v161
	v_add_f32_e32 v161, 1.0, v169
	v_mul_f32_e32 v169, 0xbfb8aa3b, v70
	v_exp_f32_e32 v171, v169
	v_mul_f32_e32 v169, 0xbfb8aa3b, v66
	v_exp_f32_e32 v173, v169
	v_rcp_f32_e32 v169, v161
	v_add_f32_e32 v161, 1.0, v171
	v_rcp_f32_e32 v171, v161
	v_add_f32_e32 v161, 1.0, v173
	v_mul_f32_e32 v173, 0xbfb8aa3b, v71
	v_exp_f32_e32 v175, v173
	v_mul_f32_e32 v173, 0xbfb8aa3b, v67
	v_exp_f32_e32 v177, v173
	v_rcp_f32_e32 v173, v161
	v_add_f32_e32 v161, 1.0, v175
	v_rcp_f32_e32 v175, v161
	v_pk_fma_f32 v[162:163], v[162:163], s[24:25], 0.5 op_sel_hi:[1,0,0]
	v_add_f32_e32 v161, 1.0, v177
	v_cvt_u32_f32_e32 v178, v163
	v_cvt_u32_f32_e32 v179, v162
	v_pk_fma_f32 v[162:163], v[166:167], s[24:25], 0.5 op_sel_hi:[1,0,0]
	v_rcp_f32_e32 v177, v161
	v_cvt_u32_f32_e32 v166, v162
	v_cvt_u32_f32_e32 v167, v163
	v_pk_fma_f32 v[162:163], v[170:171], s[24:25], 0.5 op_sel_hi:[1,0,0]
	v_pk_fma_f32 v[164:165], v[164:165], s[24:25], 0.5 op_sel_hi:[1,0,0]
	v_cvt_u32_f32_sdwa v170, v162 dst_sel:WORD_1 dst_unused:UNUSED_PAD src0_sel:DWORD
	v_cvt_u32_f32_sdwa v171, v163 dst_sel:WORD_1 dst_unused:UNUSED_PAD src0_sel:DWORD
	v_pk_fma_f32 v[162:163], v[174:175], s[24:25], 0.5 op_sel_hi:[1,0,0]
	v_lshlrev_b32_e32 v167, 8, v167
	v_cvt_u32_f32_sdwa v162, v162 dst_sel:BYTE_3 dst_unused:UNUSED_PAD src0_sel:DWORD
	v_cvt_u32_f32_sdwa v163, v163 dst_sel:BYTE_3 dst_unused:UNUSED_PAD src0_sel:DWORD
	v_lshlrev_b32_e32 v166, 8, v166
	v_or_b32_e32 v167, v167, v178
	v_or_b32_e32 v166, v166, v179
	v_or_b32_e32 v167, v167, v171
	v_or_b32_e32 v166, v166, v170
	v_or_b32_e32 v163, v167, v163
	v_or_b32_e32 v162, v166, v162
	v_cvt_u32_f32_e32 v166, v165
	v_cvt_u32_f32_e32 v167, v164
	v_pk_fma_f32 v[164:165], v[168:169], s[24:25], 0.5 op_sel_hi:[1,0,0]
	v_or_b32_e32 v161, 48, v160
	v_cvt_u32_f32_e32 v168, v164
	v_cvt_u32_f32_e32 v169, v165
	v_pk_fma_f32 v[164:165], v[172:173], s[24:25], 0.5 op_sel_hi:[1,0,0]
	v_add_u32_e32 v178, 0x80, v160
	v_cvt_u32_f32_sdwa v170, v164 dst_sel:WORD_1 dst_unused:UNUSED_PAD src0_sel:DWORD
	v_cvt_u32_f32_sdwa v171, v165 dst_sel:WORD_1 dst_unused:UNUSED_PAD src0_sel:DWORD
	v_pk_fma_f32 v[164:165], v[176:177], s[24:25], 0.5 op_sel_hi:[1,0,0]
	v_lshlrev_b32_e32 v169, 8, v169
	v_cvt_u32_f32_sdwa v164, v164 dst_sel:BYTE_3 dst_unused:UNUSED_PAD src0_sel:DWORD
	v_cvt_u32_f32_sdwa v165, v165 dst_sel:BYTE_3 dst_unused:UNUSED_PAD src0_sel:DWORD
	v_lshlrev_b32_e32 v168, 8, v168
	v_or_b32_e32 v166, v169, v166
	v_or_b32_e32 v167, v168, v167
	v_or_b32_e32 v166, v166, v171
	v_or_b32_e32 v167, v167, v170
	v_or_b32_e32 v165, v166, v165
	v_or_b32_e32 v164, v167, v164
	v_mad_i64_i32 v[166:167], s[2:3], v161, s51, v[150:151]
	v_lshl_add_u64 v[166:167], v[166:167], 0, v[148:149]
	v_add_co_u32_e32 v166, vcc, s52, v166
	v_mul_f32_e32 v161, 0xbfb8aa3b, v60
	s_nop 0
	v_addc_co_u32_e32 v167, vcc, 0, v167, vcc
	global_store_dwordx4 v[166:167], v[162:165], off offset:3072 nt
	v_exp_f32_e32 v161, v161
	s_nop 0
	v_mul_f32_e32 v162, 0xbfb8aa3b, v56
	v_exp_f32_e32 v163, v162
	v_add_f32_e32 v161, 1.0, v161
	v_rcp_f32_e32 v162, v161
	v_mul_f32_e32 v164, 0xbfb8aa3b, v57
	v_add_f32_e32 v161, 1.0, v163
	v_mul_f32_e32 v163, 0xbfb8aa3b, v61
	v_exp_f32_e32 v163, v163
	v_exp_f32_e32 v165, v164
	v_rcp_f32_e32 v164, v161
	v_add_f32_e32 v161, 1.0, v163
	v_mul_f32_e32 v163, 0xbfb8aa3b, v62
	v_rcp_f32_e32 v166, v161
	v_add_f32_e32 v161, 1.0, v165
	v_exp_f32_e32 v163, v163
	v_mul_f32_e32 v165, 0xbfb8aa3b, v58
	v_exp_f32_e32 v165, v165
	v_rcp_f32_e32 v168, v161
	v_add_f32_e32 v161, 1.0, v163
	v_mul_f32_e32 v163, 0xbfb8aa3b, v63
	v_rcp_f32_e32 v170, v161
	v_add_f32_e32 v161, 1.0, v165
	v_exp_f32_e32 v163, v163
	v_mul_f32_e32 v165, 0xbfb8aa3b, v59
	v_exp_f32_e32 v165, v165
	v_rcp_f32_e32 v172, v161
	v_add_f32_e32 v161, 1.0, v163
	v_mul_f32_e32 v163, 0xbfb8aa3b, v52
	v_rcp_f32_e32 v174, v161
	v_add_f32_e32 v161, 1.0, v165
	v_exp_f32_e32 v163, v163
	v_mul_f32_e32 v165, 0xbfb8aa3b, v48
	v_exp_f32_e32 v165, v165
	v_rcp_f32_e32 v176, v161
	v_add_f32_e32 v161, 1.0, v163
	v_rcp_f32_e32 v163, v161
	v_add_f32_e32 v161, 1.0, v165
	v_mul_f32_e32 v165, 0xbfb8aa3b, v53
	v_exp_f32_e32 v167, v165
	v_mul_f32_e32 v165, 0xbfb8aa3b, v49
	v_exp_f32_e32 v169, v165
	v_rcp_f32_e32 v165, v161
	v_add_f32_e32 v161, 1.0, v167
	v_rcp_f32_e32 v167, v161
	v_add_f32_e32 v161, 1.0, v169
	v_mul_f32_e32 v169, 0xbfb8aa3b, v54
	v_exp_f32_e32 v171, v169
	v_mul_f32_e32 v169, 0xbfb8aa3b, v50
	v_exp_f32_e32 v173, v169
	v_rcp_f32_e32 v169, v161
	v_add_f32_e32 v161, 1.0, v171
	v_rcp_f32_e32 v171, v161
	v_add_f32_e32 v161, 1.0, v173
	v_mul_f32_e32 v173, 0xbfb8aa3b, v55
	v_exp_f32_e32 v175, v173
	v_mul_f32_e32 v173, 0xbfb8aa3b, v51
	v_exp_f32_e32 v177, v173
	v_rcp_f32_e32 v173, v161
	v_add_f32_e32 v161, 1.0, v175
	v_rcp_f32_e32 v175, v161
	v_add_f32_e32 v161, 1.0, v177
	v_pk_fma_f32 v[162:163], v[162:163], s[24:25], 0.5 op_sel_hi:[1,0,0]
	v_rcp_f32_e32 v177, v161
	v_cvt_u32_f32_e32 v161, v163
	v_cvt_u32_f32_e32 v179, v162
	v_pk_fma_f32 v[162:163], v[166:167], s[24:25], 0.5 op_sel_hi:[1,0,0]
	v_pk_fma_f32 v[164:165], v[164:165], s[24:25], 0.5 op_sel_hi:[1,0,0]
	v_cvt_u32_f32_e32 v166, v162
	v_cvt_u32_f32_e32 v167, v163
	v_pk_fma_f32 v[162:163], v[170:171], s[24:25], 0.5 op_sel_hi:[1,0,0]
	v_lshlrev_b32_e32 v166, 8, v166
	v_cvt_u32_f32_sdwa v170, v162 dst_sel:WORD_1 dst_unused:UNUSED_PAD src0_sel:DWORD
	v_cvt_u32_f32_sdwa v171, v163 dst_sel:WORD_1 dst_unused:UNUSED_PAD src0_sel:DWORD
	v_pk_fma_f32 v[162:163], v[174:175], s[24:25], 0.5 op_sel_hi:[1,0,0]
	v_lshlrev_b32_e32 v167, 8, v167
	v_cvt_u32_f32_sdwa v162, v162 dst_sel:BYTE_3 dst_unused:UNUSED_PAD src0_sel:DWORD
	v_cvt_u32_f32_sdwa v163, v163 dst_sel:BYTE_3 dst_unused:UNUSED_PAD src0_sel:DWORD
	v_or_b32_e32 v161, v167, v161
	v_or_b32_e32 v166, v166, v179
	v_or_b32_e32 v161, v161, v171
	v_or_b32_e32 v166, v166, v170
	v_or_b32_e32 v163, v161, v163
	v_or_b32_e32 v162, v166, v162
	v_cvt_u32_f32_e32 v161, v165
	v_cvt_u32_f32_e32 v166, v164
	v_pk_fma_f32 v[164:165], v[168:169], s[24:25], 0.5 op_sel_hi:[1,0,0]
	s_nop 0
	v_cvt_u32_f32_e32 v167, v164
	v_cvt_u32_f32_e32 v168, v165
	v_pk_fma_f32 v[164:165], v[172:173], s[24:25], 0.5 op_sel_hi:[1,0,0]
	v_lshlrev_b32_e32 v167, 8, v167
	v_cvt_u32_f32_sdwa v169, v164 dst_sel:WORD_1 dst_unused:UNUSED_PAD src0_sel:DWORD
	v_cvt_u32_f32_sdwa v170, v165 dst_sel:WORD_1 dst_unused:UNUSED_PAD src0_sel:DWORD
	v_pk_fma_f32 v[164:165], v[176:177], s[24:25], 0.5 op_sel_hi:[1,0,0]
	v_or_b32_e32 v166, v167, v166
	v_cvt_u32_f32_sdwa v164, v164 dst_sel:BYTE_3 dst_unused:UNUSED_PAD src0_sel:DWORD
	v_cvt_u32_f32_sdwa v165, v165 dst_sel:BYTE_3 dst_unused:UNUSED_PAD src0_sel:DWORD
	v_lshlrev_b32_e32 v168, 8, v168
	v_or_b32_e32 v166, v166, v169
	v_or_b32_e32 v161, v168, v161
	v_or_b32_e32 v164, v166, v164
	v_mad_i64_i32 v[166:167], s[2:3], v178, s51, v[150:151]
	v_or_b32_e32 v161, v161, v170
	v_lshl_add_u64 v[166:167], v[166:167], 0, v[148:149]
	v_or_b32_e32 v165, v161, v165
	v_add_co_u32_e32 v166, vcc, s52, v166
	v_mul_f32_e32 v161, 0xbfb8aa3b, v44
	s_nop 0
	v_addc_co_u32_e32 v167, vcc, 0, v167, vcc
	v_exp_f32_e32 v161, v161
	v_mul_f32_e32 v168, 0xbfb8aa3b, v40
	v_exp_f32_e32 v168, v168
	global_store_dwordx4 v[166:167], v[162:165], off offset:3072 nt
	v_add_f32_e32 v161, 1.0, v161
	s_nop 0
	v_mul_f32_e32 v163, 0xbfb8aa3b, v45
	v_exp_f32_e32 v163, v163
	v_mul_f32_e32 v164, 0xbfb8aa3b, v41
	v_exp_f32_e32 v165, v164
	v_rcp_f32_e32 v162, v161
	v_add_f32_e32 v161, 1.0, v168
	v_rcp_f32_e32 v164, v161
	v_add_f32_e32 v161, 1.0, v163
	v_mul_f32_e32 v163, 0xbfb8aa3b, v46
	v_rcp_f32_e32 v166, v161
	v_add_f32_e32 v161, 1.0, v165
	v_exp_f32_e32 v163, v163
	v_mul_f32_e32 v165, 0xbfb8aa3b, v42
	v_exp_f32_e32 v165, v165
	v_rcp_f32_e32 v168, v161
	v_add_f32_e32 v161, 1.0, v163
	v_mul_f32_e32 v163, 0xbfb8aa3b, v47
	v_rcp_f32_e32 v170, v161
	v_add_f32_e32 v161, 1.0, v165
	v_exp_f32_e32 v163, v163
	v_mul_f32_e32 v165, 0xbfb8aa3b, v43
	v_exp_f32_e32 v165, v165
	v_rcp_f32_e32 v172, v161
	v_add_f32_e32 v161, 1.0, v163
	v_mul_f32_e32 v163, 0xbfb8aa3b, v36
	v_rcp_f32_e32 v174, v161
	v_add_f32_e32 v161, 1.0, v165
	v_exp_f32_e32 v163, v163
	v_mul_f32_e32 v165, 0xbfb8aa3b, v32
	v_exp_f32_e32 v165, v165
	v_rcp_f32_e32 v176, v161
	v_add_f32_e32 v161, 1.0, v163
	v_rcp_f32_e32 v163, v161
	v_add_f32_e32 v161, 1.0, v165
	v_mul_f32_e32 v165, 0xbfb8aa3b, v37
	v_exp_f32_e32 v167, v165
	v_mul_f32_e32 v165, 0xbfb8aa3b, v33
	v_exp_f32_e32 v169, v165
	v_rcp_f32_e32 v165, v161
	v_add_f32_e32 v161, 1.0, v167
	v_rcp_f32_e32 v167, v161
	v_add_f32_e32 v161, 1.0, v169
	v_mul_f32_e32 v169, 0xbfb8aa3b, v38
	v_exp_f32_e32 v171, v169
	v_mul_f32_e32 v169, 0xbfb8aa3b, v34
	v_exp_f32_e32 v173, v169
	v_rcp_f32_e32 v169, v161
	v_add_f32_e32 v161, 1.0, v171
	v_rcp_f32_e32 v171, v161
	v_add_f32_e32 v161, 1.0, v173
	v_mul_f32_e32 v173, 0xbfb8aa3b, v39
	v_exp_f32_e32 v175, v173
	v_mul_f32_e32 v173, 0xbfb8aa3b, v35
	v_exp_f32_e32 v177, v173
	v_rcp_f32_e32 v173, v161
	v_add_f32_e32 v161, 1.0, v175
	v_rcp_f32_e32 v175, v161
	v_pk_fma_f32 v[162:163], v[162:163], s[24:25], 0.5 op_sel_hi:[1,0,0]
	v_add_f32_e32 v161, 1.0, v177
	v_cvt_u32_f32_e32 v178, v163
	v_cvt_u32_f32_e32 v179, v162
	v_pk_fma_f32 v[162:163], v[166:167], s[24:25], 0.5 op_sel_hi:[1,0,0]
	v_rcp_f32_e32 v177, v161
	v_cvt_u32_f32_e32 v166, v162
	v_cvt_u32_f32_e32 v167, v163
	v_pk_fma_f32 v[162:163], v[170:171], s[24:25], 0.5 op_sel_hi:[1,0,0]
	v_pk_fma_f32 v[164:165], v[164:165], s[24:25], 0.5 op_sel_hi:[1,0,0]
	v_cvt_u32_f32_sdwa v170, v162 dst_sel:WORD_1 dst_unused:UNUSED_PAD src0_sel:DWORD
	v_cvt_u32_f32_sdwa v171, v163 dst_sel:WORD_1 dst_unused:UNUSED_PAD src0_sel:DWORD
	v_pk_fma_f32 v[162:163], v[174:175], s[24:25], 0.5 op_sel_hi:[1,0,0]
	v_lshlrev_b32_e32 v167, 8, v167
	v_cvt_u32_f32_sdwa v162, v162 dst_sel:BYTE_3 dst_unused:UNUSED_PAD src0_sel:DWORD
	v_cvt_u32_f32_sdwa v163, v163 dst_sel:BYTE_3 dst_unused:UNUSED_PAD src0_sel:DWORD
	v_lshlrev_b32_e32 v166, 8, v166
	v_or_b32_e32 v167, v167, v178
	v_or_b32_e32 v166, v166, v179
	v_or_b32_e32 v167, v167, v171
	v_or_b32_e32 v166, v166, v170
	v_or_b32_e32 v163, v167, v163
	v_or_b32_e32 v162, v166, v162
	v_cvt_u32_f32_e32 v166, v165
	v_cvt_u32_f32_e32 v167, v164
	v_pk_fma_f32 v[164:165], v[168:169], s[24:25], 0.5 op_sel_hi:[1,0,0]
	v_add_u32_e32 v161, 0x90, v160
	v_cvt_u32_f32_e32 v168, v164
	v_cvt_u32_f32_e32 v169, v165
	v_pk_fma_f32 v[164:165], v[172:173], s[24:25], 0.5 op_sel_hi:[1,0,0]
	v_lshlrev_b32_e32 v168, 8, v168
	v_cvt_u32_f32_sdwa v170, v164 dst_sel:WORD_1 dst_unused:UNUSED_PAD src0_sel:DWORD
	v_cvt_u32_f32_sdwa v171, v165 dst_sel:WORD_1 dst_unused:UNUSED_PAD src0_sel:DWORD
	v_pk_fma_f32 v[164:165], v[176:177], s[24:25], 0.5 op_sel_hi:[1,0,0]
	v_lshlrev_b32_e32 v169, 8, v169
	v_cvt_u32_f32_sdwa v164, v164 dst_sel:BYTE_3 dst_unused:UNUSED_PAD src0_sel:DWORD
	v_cvt_u32_f32_sdwa v165, v165 dst_sel:BYTE_3 dst_unused:UNUSED_PAD src0_sel:DWORD
	v_or_b32_e32 v166, v169, v166
	v_or_b32_e32 v167, v168, v167
	v_or_b32_e32 v166, v166, v171
	v_or_b32_e32 v167, v167, v170
	v_or_b32_e32 v165, v166, v165
	v_or_b32_e32 v164, v167, v164
	v_mad_i64_i32 v[166:167], s[2:3], v161, s51, v[150:151]
	v_lshl_add_u64 v[166:167], v[166:167], 0, v[148:149]
	v_add_co_u32_e32 v166, vcc, s52, v166
	v_mul_f32_e32 v161, 0xbfb8aa3b, v28
	s_nop 0
	v_addc_co_u32_e32 v167, vcc, 0, v167, vcc
	v_exp_f32_e32 v161, v161
	v_mul_f32_e32 v168, 0xbfb8aa3b, v24
	v_exp_f32_e32 v168, v168
	global_store_dwordx4 v[166:167], v[162:165], off offset:3072 nt
	v_add_f32_e32 v161, 1.0, v161
	s_nop 0
	v_mul_f32_e32 v163, 0xbfb8aa3b, v29
	v_exp_f32_e32 v163, v163
	v_mul_f32_e32 v164, 0xbfb8aa3b, v25
	v_exp_f32_e32 v165, v164
	v_rcp_f32_e32 v162, v161
	v_add_f32_e32 v161, 1.0, v168
	v_rcp_f32_e32 v164, v161
	v_add_f32_e32 v161, 1.0, v163
	v_mul_f32_e32 v163, 0xbfb8aa3b, v30
	v_rcp_f32_e32 v166, v161
	v_add_f32_e32 v161, 1.0, v165
	v_exp_f32_e32 v163, v163
	v_mul_f32_e32 v165, 0xbfb8aa3b, v26
	v_exp_f32_e32 v165, v165
	v_rcp_f32_e32 v168, v161
	v_add_f32_e32 v161, 1.0, v163
	v_mul_f32_e32 v163, 0xbfb8aa3b, v31
	v_rcp_f32_e32 v170, v161
	v_add_f32_e32 v161, 1.0, v165
	v_exp_f32_e32 v163, v163
	v_mul_f32_e32 v165, 0xbfb8aa3b, v27
	v_exp_f32_e32 v165, v165
	v_rcp_f32_e32 v172, v161
	v_add_f32_e32 v161, 1.0, v163
	v_mul_f32_e32 v163, 0xbfb8aa3b, v20
	v_rcp_f32_e32 v174, v161
	v_add_f32_e32 v161, 1.0, v165
	v_exp_f32_e32 v163, v163
	v_mul_f32_e32 v165, 0xbfb8aa3b, v16
	v_exp_f32_e32 v165, v165
	v_rcp_f32_e32 v176, v161
	v_add_f32_e32 v161, 1.0, v163
	v_rcp_f32_e32 v163, v161
	v_add_f32_e32 v161, 1.0, v165
	v_mul_f32_e32 v165, 0xbfb8aa3b, v21
	v_exp_f32_e32 v167, v165
	v_mul_f32_e32 v165, 0xbfb8aa3b, v17
	v_exp_f32_e32 v169, v165
	v_rcp_f32_e32 v165, v161
	v_add_f32_e32 v161, 1.0, v167
	v_rcp_f32_e32 v167, v161
	v_add_f32_e32 v161, 1.0, v169
	v_mul_f32_e32 v169, 0xbfb8aa3b, v22
	v_exp_f32_e32 v171, v169
	v_mul_f32_e32 v169, 0xbfb8aa3b, v18
	v_exp_f32_e32 v173, v169
	v_rcp_f32_e32 v169, v161
	v_add_f32_e32 v161, 1.0, v171
	v_rcp_f32_e32 v171, v161
	v_add_f32_e32 v161, 1.0, v173
	v_mul_f32_e32 v173, 0xbfb8aa3b, v23
	v_exp_f32_e32 v175, v173
	v_mul_f32_e32 v173, 0xbfb8aa3b, v19
	v_exp_f32_e32 v177, v173
	v_rcp_f32_e32 v173, v161
	v_add_f32_e32 v161, 1.0, v175
	v_rcp_f32_e32 v175, v161
	v_pk_fma_f32 v[162:163], v[162:163], s[24:25], 0.5 op_sel_hi:[1,0,0]
	v_add_f32_e32 v161, 1.0, v177
	v_cvt_u32_f32_e32 v178, v163
	v_cvt_u32_f32_e32 v179, v162
	v_pk_fma_f32 v[162:163], v[166:167], s[24:25], 0.5 op_sel_hi:[1,0,0]
	v_rcp_f32_e32 v177, v161
	v_cvt_u32_f32_e32 v166, v162
	v_cvt_u32_f32_e32 v167, v163
	v_pk_fma_f32 v[162:163], v[170:171], s[24:25], 0.5 op_sel_hi:[1,0,0]
	v_pk_fma_f32 v[164:165], v[164:165], s[24:25], 0.5 op_sel_hi:[1,0,0]
	v_cvt_u32_f32_sdwa v170, v162 dst_sel:WORD_1 dst_unused:UNUSED_PAD src0_sel:DWORD
	v_cvt_u32_f32_sdwa v171, v163 dst_sel:WORD_1 dst_unused:UNUSED_PAD src0_sel:DWORD
	v_pk_fma_f32 v[162:163], v[174:175], s[24:25], 0.5 op_sel_hi:[1,0,0]
	v_lshlrev_b32_e32 v167, 8, v167
	v_cvt_u32_f32_sdwa v162, v162 dst_sel:BYTE_3 dst_unused:UNUSED_PAD src0_sel:DWORD
	v_cvt_u32_f32_sdwa v163, v163 dst_sel:BYTE_3 dst_unused:UNUSED_PAD src0_sel:DWORD
	v_lshlrev_b32_e32 v166, 8, v166
	v_or_b32_e32 v167, v167, v178
	v_or_b32_e32 v166, v166, v179
	v_or_b32_e32 v167, v167, v171
	v_or_b32_e32 v166, v166, v170
	v_or_b32_e32 v163, v167, v163
	v_or_b32_e32 v162, v166, v162
	v_cvt_u32_f32_e32 v166, v165
	v_cvt_u32_f32_e32 v167, v164
	v_pk_fma_f32 v[164:165], v[168:169], s[24:25], 0.5 op_sel_hi:[1,0,0]
	v_add_u32_e32 v161, 0xa0, v160
	v_cvt_u32_f32_e32 v168, v164
	v_cvt_u32_f32_e32 v169, v165
	v_pk_fma_f32 v[164:165], v[172:173], s[24:25], 0.5 op_sel_hi:[1,0,0]
	v_lshlrev_b32_e32 v168, 8, v168
	v_cvt_u32_f32_sdwa v170, v164 dst_sel:WORD_1 dst_unused:UNUSED_PAD src0_sel:DWORD
	v_cvt_u32_f32_sdwa v171, v165 dst_sel:WORD_1 dst_unused:UNUSED_PAD src0_sel:DWORD
	v_pk_fma_f32 v[164:165], v[176:177], s[24:25], 0.5 op_sel_hi:[1,0,0]
	v_lshlrev_b32_e32 v169, 8, v169
	v_cvt_u32_f32_sdwa v164, v164 dst_sel:BYTE_3 dst_unused:UNUSED_PAD src0_sel:DWORD
	v_cvt_u32_f32_sdwa v165, v165 dst_sel:BYTE_3 dst_unused:UNUSED_PAD src0_sel:DWORD
	v_or_b32_e32 v166, v169, v166
	v_or_b32_e32 v167, v168, v167
	v_or_b32_e32 v166, v166, v171
	v_or_b32_e32 v167, v167, v170
	v_or_b32_e32 v165, v166, v165
	v_or_b32_e32 v164, v167, v164
	v_mad_i64_i32 v[166:167], s[2:3], v161, s51, v[150:151]
	v_lshl_add_u64 v[166:167], v[166:167], 0, v[148:149]
	v_add_co_u32_e32 v166, vcc, s52, v166
	v_mul_f32_e32 v161, 0xbfb8aa3b, v12
	s_nop 0
	v_addc_co_u32_e32 v167, vcc, 0, v167, vcc
	v_exp_f32_e32 v161, v161
	v_mul_f32_e32 v168, 0xbfb8aa3b, v8
	v_exp_f32_e32 v168, v168
	global_store_dwordx4 v[166:167], v[162:165], off offset:3072 nt
	v_add_f32_e32 v161, 1.0, v161
	s_nop 0
	v_mul_f32_e32 v163, 0xbfb8aa3b, v13
	v_exp_f32_e32 v163, v163
	v_mul_f32_e32 v164, 0xbfb8aa3b, v9
	v_exp_f32_e32 v165, v164
	v_rcp_f32_e32 v162, v161
	v_add_f32_e32 v161, 1.0, v168
	v_rcp_f32_e32 v164, v161
	v_add_f32_e32 v161, 1.0, v163
	v_mul_f32_e32 v163, 0xbfb8aa3b, v14
	v_rcp_f32_e32 v166, v161
	v_add_f32_e32 v161, 1.0, v165
	v_exp_f32_e32 v163, v163
	v_mul_f32_e32 v165, 0xbfb8aa3b, v10
	v_exp_f32_e32 v165, v165
	v_rcp_f32_e32 v168, v161
	v_add_f32_e32 v161, 1.0, v163
	v_mul_f32_e32 v163, 0xbfb8aa3b, v15
	v_rcp_f32_e32 v170, v161
	v_add_f32_e32 v161, 1.0, v165
	v_exp_f32_e32 v163, v163
	v_mul_f32_e32 v165, 0xbfb8aa3b, v11
	v_exp_f32_e32 v165, v165
	v_rcp_f32_e32 v172, v161
	v_add_f32_e32 v161, 1.0, v163
	v_mul_f32_e32 v163, 0xbfb8aa3b, v4
	v_rcp_f32_e32 v174, v161
	v_add_f32_e32 v161, 1.0, v165
	v_exp_f32_e32 v163, v163
	v_mul_f32_e32 v165, 0xbfb8aa3b, v0
	v_exp_f32_e32 v165, v165
	v_rcp_f32_e32 v176, v161
	v_add_f32_e32 v161, 1.0, v163
	v_rcp_f32_e32 v163, v161
	v_add_f32_e32 v161, 1.0, v165
	v_mul_f32_e32 v165, 0xbfb8aa3b, v5
	v_exp_f32_e32 v167, v165
	v_mul_f32_e32 v165, 0xbfb8aa3b, v1
	v_exp_f32_e32 v169, v165
	v_rcp_f32_e32 v165, v161
	v_add_f32_e32 v161, 1.0, v167
	v_rcp_f32_e32 v167, v161
	v_add_f32_e32 v161, 1.0, v169
	v_mul_f32_e32 v169, 0xbfb8aa3b, v6
	v_exp_f32_e32 v171, v169
	v_mul_f32_e32 v169, 0xbfb8aa3b, v2
	v_exp_f32_e32 v173, v169
	v_rcp_f32_e32 v169, v161
	v_add_f32_e32 v161, 1.0, v171
	v_rcp_f32_e32 v171, v161
	v_add_f32_e32 v161, 1.0, v173
	v_mul_f32_e32 v173, 0xbfb8aa3b, v7
	v_exp_f32_e32 v175, v173
	v_mul_f32_e32 v173, 0xbfb8aa3b, v3
	v_exp_f32_e32 v177, v173
	v_rcp_f32_e32 v173, v161
	v_add_f32_e32 v161, 1.0, v175
	v_rcp_f32_e32 v175, v161
	v_pk_fma_f32 v[162:163], v[162:163], s[24:25], 0.5 op_sel_hi:[1,0,0]
	v_add_f32_e32 v161, 1.0, v177
	v_cvt_u32_f32_e32 v178, v163
	v_cvt_u32_f32_e32 v179, v162
	v_pk_fma_f32 v[162:163], v[166:167], s[24:25], 0.5 op_sel_hi:[1,0,0]
	v_rcp_f32_e32 v177, v161
	v_cvt_u32_f32_e32 v166, v162
	v_cvt_u32_f32_e32 v167, v163
	v_pk_fma_f32 v[162:163], v[170:171], s[24:25], 0.5 op_sel_hi:[1,0,0]
	v_pk_fma_f32 v[164:165], v[164:165], s[24:25], 0.5 op_sel_hi:[1,0,0]
	v_cvt_u32_f32_sdwa v170, v162 dst_sel:WORD_1 dst_unused:UNUSED_PAD src0_sel:DWORD
	v_cvt_u32_f32_sdwa v171, v163 dst_sel:WORD_1 dst_unused:UNUSED_PAD src0_sel:DWORD
	v_pk_fma_f32 v[162:163], v[174:175], s[24:25], 0.5 op_sel_hi:[1,0,0]
	v_lshlrev_b32_e32 v167, 8, v167
	v_cvt_u32_f32_sdwa v162, v162 dst_sel:BYTE_3 dst_unused:UNUSED_PAD src0_sel:DWORD
	v_cvt_u32_f32_sdwa v163, v163 dst_sel:BYTE_3 dst_unused:UNUSED_PAD src0_sel:DWORD
	v_lshlrev_b32_e32 v166, 8, v166
	v_or_b32_e32 v167, v167, v178
	v_or_b32_e32 v166, v166, v179
	v_or_b32_e32 v167, v167, v171
	v_or_b32_e32 v166, v166, v170
	v_or_b32_e32 v163, v167, v163
	v_or_b32_e32 v162, v166, v162
	v_cvt_u32_f32_e32 v166, v165
	v_cvt_u32_f32_e32 v167, v164
	v_pk_fma_f32 v[164:165], v[168:169], s[24:25], 0.5 op_sel_hi:[1,0,0]
	v_add_u32_e32 v161, 0xb0, v160
	v_cvt_u32_f32_e32 v168, v164
	v_cvt_u32_f32_e32 v169, v165
	v_pk_fma_f32 v[164:165], v[172:173], s[24:25], 0.5 op_sel_hi:[1,0,0]
	v_mad_i64_i32 v[150:151], s[2:3], v161, s51, v[150:151]
	v_cvt_u32_f32_sdwa v170, v164 dst_sel:WORD_1 dst_unused:UNUSED_PAD src0_sel:DWORD
	v_cvt_u32_f32_sdwa v171, v165 dst_sel:WORD_1 dst_unused:UNUSED_PAD src0_sel:DWORD
	v_pk_fma_f32 v[164:165], v[176:177], s[24:25], 0.5 op_sel_hi:[1,0,0]
	v_lshlrev_b32_e32 v169, 8, v169
	v_cvt_u32_f32_sdwa v164, v164 dst_sel:BYTE_3 dst_unused:UNUSED_PAD src0_sel:DWORD
	v_cvt_u32_f32_sdwa v165, v165 dst_sel:BYTE_3 dst_unused:UNUSED_PAD src0_sel:DWORD
	v_lshlrev_b32_e32 v168, 8, v168
	v_or_b32_e32 v166, v169, v166
	v_or_b32_e32 v167, v168, v167
	v_lshl_add_u64 v[148:149], v[150:151], 0, v[148:149]
	v_or_b32_e32 v166, v166, v171
	v_or_b32_e32 v167, v167, v170
	v_add_co_u32_e32 v148, vcc, 0x1000, v148
	v_or_b32_e32 v165, v166, v165
	v_or_b32_e32 v164, v167, v164
	v_addc_co_u32_e32 v149, vcc, 0, v149, vcc
	global_store_dwordx4 v[148:149], v[162:165], off offset:3072 nt
	s_mov_b64 s[2:3], 0

.LBB0_224:
	v_readlane_b32 s10, v246, 26
	v_readlane_b32 s11, v246, 27
	v_cvt_pk_bf16_f32 v168, v150, v161
	v_cndmask_b32_e64 v150, 0, 1, s[2:3]
	v_cvt_pk_bf16_f32 v169, v162, v165
	v_cvt_pk_bf16_f32 v170, v151, v163
	v_cvt_pk_bf16_f32 v171, v164, v166
	s_nop 0
	v_mov_b64_e32 v[148:149], s[10:11]
	v_mad_i64_i32 v[148:149], s[10:11], v160, s51, v[148:149]
	v_lshl_add_u64 v[148:149], v[136:137], 1, v[148:149]
	v_cmp_ne_u32_e64 s[10:11], 1, v150
	s_andn2_b64 vcc, exec, s[2:3]
	v_mov_b32_e32 v150, v116
	v_mov_b32_e32 v161, v117
	v_mov_b32_e32 v162, v118
	v_mov_b32_e32 v165, v119
	v_mov_b32_e32 v151, v112
	v_mov_b32_e32 v163, v113
	v_mov_b32_e32 v164, v114
	v_mov_b32_e32 v166, v115
	global_store_dwordx4 v[148:149], v[168:171], off nt
	s_cbranch_vccnz .LBB0_226
	v_mul_f32_e32 v162, 0xbfb8aa3b, v113
	v_mul_f32_e32 v163, 0xbfb8aa3b, v118
	v_exp_f32_e32 v162, v162
	v_exp_f32_e32 v164, v163
	v_mul_f32_e32 v163, 0xbfb8aa3b, v114
	v_exp_f32_e32 v165, v163
	v_add_f32_e32 v162, 1.0, v162
	v_mul_f32_e32 v150, 0xbfb8aa3b, v116
	v_mul_f32_e32 v151, 0xbfb8aa3b, v112
	v_mul_f32_e32 v161, 0xbfb8aa3b, v117
	v_rcp_f32_e32 v163, v162
	v_add_f32_e32 v162, 1.0, v164
	v_add_f32_e32 v164, 1.0, v165
	v_mul_f32_e32 v165, 0xbfb8aa3b, v119
	v_mul_f32_e32 v166, 0xbfb8aa3b, v115
	v_exp_f32_e32 v150, v150
	v_exp_f32_e32 v151, v151
	v_exp_f32_e32 v161, v161
	v_exp_f32_e32 v165, v165
	v_exp_f32_e32 v166, v166
	v_add_f32_e32 v150, 1.0, v150
	v_add_f32_e32 v151, 1.0, v151
	v_add_f32_e32 v161, 1.0, v161
	v_add_f32_e32 v165, 1.0, v165
	v_add_f32_e32 v166, 1.0, v166
	v_rcp_f32_e32 v150, v150
	v_rcp_f32_e32 v151, v151
	v_rcp_f32_e32 v161, v161
	v_rcp_f32_e32 v162, v162
	v_rcp_f32_e32 v164, v164
	v_rcp_f32_e32 v165, v165
	v_rcp_f32_e32 v166, v166
.LBB0_226:
	s_nop 0
	v_cvt_pk_bf16_f32 v168, v150, v161
	v_cvt_pk_bf16_f32 v169, v162, v165
	v_cvt_pk_bf16_f32 v170, v151, v163
	v_cvt_pk_bf16_f32 v171, v164, v166
	s_and_b64 vcc, exec, s[10:11]
	v_mov_b32_e32 v150, v108
	v_mov_b32_e32 v161, v109
	v_mov_b32_e32 v162, v110
	v_mov_b32_e32 v165, v111
	v_mov_b32_e32 v151, v104
	v_mov_b32_e32 v163, v105
	v_mov_b32_e32 v164, v106
	v_mov_b32_e32 v166, v107
	global_store_dwordx4 v[148:149], v[168:171], off offset:256 nt
	s_cbranch_vccnz .LBB0_228
	v_mul_f32_e32 v148, 0xbfb8aa3b, v108
	v_exp_f32_e32 v148, v148
	v_mul_f32_e32 v149, 0xbfb8aa3b, v104
	v_exp_f32_e32 v149, v149
	v_mul_f32_e32 v151, 0xbfb8aa3b, v105
	v_add_f32_e32 v148, 1.0, v148
	v_rcp_f32_e32 v150, v148
	v_mul_f32_e32 v148, 0xbfb8aa3b, v109
	v_exp_f32_e32 v148, v148
	v_exp_f32_e32 v162, v151
	v_add_f32_e32 v149, 1.0, v149
	v_rcp_f32_e32 v151, v149
	v_add_f32_e32 v148, 1.0, v148
	v_mul_f32_e32 v149, 0xbfb8aa3b, v110
	v_rcp_f32_e32 v161, v148
	v_add_f32_e32 v148, 1.0, v162
	v_exp_f32_e32 v149, v149
	v_mul_f32_e32 v162, 0xbfb8aa3b, v106
	v_exp_f32_e32 v164, v162
	v_rcp_f32_e32 v163, v148
	v_add_f32_e32 v148, 1.0, v149
	v_mul_f32_e32 v149, 0xbfb8aa3b, v111
	v_rcp_f32_e32 v162, v148
	v_add_f32_e32 v148, 1.0, v164
	v_exp_f32_e32 v149, v149
	v_mul_f32_e32 v164, 0xbfb8aa3b, v107
	v_exp_f32_e32 v166, v164
	v_rcp_f32_e32 v164, v148
	v_add_f32_e32 v148, 1.0, v149
	v_rcp_f32_e32 v165, v148
	v_add_f32_e32 v148, 1.0, v166
	v_rcp_f32_e32 v166, v148
.LBB0_228:
	v_readlane_b32 s2, v246, 26
	v_readlane_b32 s3, v246, 27
	v_or_b32_e32 v167, 16, v160
	v_cvt_pk_bf16_f32 v168, v150, v161
	v_cvt_pk_bf16_f32 v169, v162, v165
	v_cvt_pk_bf16_f32 v170, v151, v163
	v_cvt_pk_bf16_f32 v171, v164, v166
	s_nop 0
	v_mov_b64_e32 v[148:149], s[2:3]
	v_mad_i64_i32 v[148:149], s[2:3], v167, s51, v[148:149]
	v_lshl_add_u64 v[148:149], v[136:137], 1, v[148:149]
	s_and_b64 vcc, exec, s[10:11]
	v_mov_b32_e32 v150, v100
	v_mov_b32_e32 v161, v101
	v_mov_b32_e32 v162, v102
	v_mov_b32_e32 v165, v103
	v_mov_b32_e32 v151, v96
	v_mov_b32_e32 v163, v97
	v_mov_b32_e32 v164, v98
	v_mov_b32_e32 v166, v99
	global_store_dwordx4 v[148:149], v[168:171], off nt
	s_cbranch_vccnz .LBB0_230
	v_mul_f32_e32 v162, 0xbfb8aa3b, v97
	v_mul_f32_e32 v163, 0xbfb8aa3b, v102
	v_exp_f32_e32 v162, v162
	v_exp_f32_e32 v164, v163
	v_mul_f32_e32 v163, 0xbfb8aa3b, v98
	v_exp_f32_e32 v165, v163
	v_add_f32_e32 v162, 1.0, v162
	v_mul_f32_e32 v150, 0xbfb8aa3b, v100
	v_mul_f32_e32 v151, 0xbfb8aa3b, v96
	v_mul_f32_e32 v161, 0xbfb8aa3b, v101
	v_rcp_f32_e32 v163, v162
	v_add_f32_e32 v162, 1.0, v164
	v_add_f32_e32 v164, 1.0, v165
	v_mul_f32_e32 v165, 0xbfb8aa3b, v103
	v_mul_f32_e32 v166, 0xbfb8aa3b, v99
	v_exp_f32_e32 v150, v150
	v_exp_f32_e32 v151, v151
	v_exp_f32_e32 v161, v161
	v_exp_f32_e32 v165, v165
	v_exp_f32_e32 v166, v166
	v_add_f32_e32 v150, 1.0, v150
	v_add_f32_e32 v151, 1.0, v151
	v_add_f32_e32 v161, 1.0, v161
	v_add_f32_e32 v165, 1.0, v165
	v_add_f32_e32 v166, 1.0, v166
	v_rcp_f32_e32 v150, v150
	v_rcp_f32_e32 v151, v151
	v_rcp_f32_e32 v161, v161
	v_rcp_f32_e32 v162, v162
	v_rcp_f32_e32 v164, v164
	v_rcp_f32_e32 v165, v165
	v_rcp_f32_e32 v166, v166
.LBB0_230:
	s_nop 0
	v_cvt_pk_bf16_f32 v168, v150, v161
	v_cvt_pk_bf16_f32 v169, v162, v165
	v_cvt_pk_bf16_f32 v170, v151, v163
	v_cvt_pk_bf16_f32 v171, v164, v166
	s_and_b64 vcc, exec, s[10:11]
	v_mov_b32_e32 v150, v92
	v_mov_b32_e32 v161, v93
	v_mov_b32_e32 v162, v94
	v_mov_b32_e32 v165, v95
	v_mov_b32_e32 v151, v88
	v_mov_b32_e32 v163, v89
	v_mov_b32_e32 v164, v90
	v_mov_b32_e32 v166, v91
	global_store_dwordx4 v[148:149], v[168:171], off offset:256 nt
	s_cbranch_vccnz .LBB0_232
	v_mul_f32_e32 v148, 0xbfb8aa3b, v92
	v_exp_f32_e32 v148, v148
	v_mul_f32_e32 v149, 0xbfb8aa3b, v88
	v_exp_f32_e32 v149, v149
	v_mul_f32_e32 v151, 0xbfb8aa3b, v89
	v_add_f32_e32 v148, 1.0, v148
	v_rcp_f32_e32 v150, v148
	v_mul_f32_e32 v148, 0xbfb8aa3b, v93
	v_exp_f32_e32 v148, v148
	v_exp_f32_e32 v162, v151
	v_add_f32_e32 v149, 1.0, v149
	v_rcp_f32_e32 v151, v149
	v_add_f32_e32 v148, 1.0, v148
	v_mul_f32_e32 v149, 0xbfb8aa3b, v94
	v_rcp_f32_e32 v161, v148
	v_add_f32_e32 v148, 1.0, v162
	v_exp_f32_e32 v149, v149
	v_mul_f32_e32 v162, 0xbfb8aa3b, v90
	v_exp_f32_e32 v164, v162
	v_rcp_f32_e32 v163, v148
	v_add_f32_e32 v148, 1.0, v149
	v_mul_f32_e32 v149, 0xbfb8aa3b, v95
	v_rcp_f32_e32 v162, v148
	v_add_f32_e32 v148, 1.0, v164
	v_exp_f32_e32 v149, v149
	v_mul_f32_e32 v164, 0xbfb8aa3b, v91
	v_exp_f32_e32 v166, v164
	v_rcp_f32_e32 v164, v148
	v_add_f32_e32 v148, 1.0, v149
	v_rcp_f32_e32 v165, v148
	v_add_f32_e32 v148, 1.0, v166
	v_rcp_f32_e32 v166, v148
.LBB0_232:
	v_readlane_b32 s2, v246, 26
	v_readlane_b32 s3, v246, 27
	v_or_b32_e32 v167, 32, v160
	v_cvt_pk_bf16_f32 v168, v150, v161
	v_cvt_pk_bf16_f32 v169, v162, v165
	v_cvt_pk_bf16_f32 v170, v151, v163
	v_cvt_pk_bf16_f32 v171, v164, v166
	s_nop 0
	v_mov_b64_e32 v[148:149], s[2:3]
	v_mad_i64_i32 v[148:149], s[2:3], v167, s51, v[148:149]
	v_lshl_add_u64 v[148:149], v[136:137], 1, v[148:149]
	s_and_b64 vcc, exec, s[10:11]
	v_mov_b32_e32 v150, v84
	v_mov_b32_e32 v161, v85
	v_mov_b32_e32 v162, v86
	v_mov_b32_e32 v165, v87
	v_mov_b32_e32 v151, v80
	v_mov_b32_e32 v163, v81
	v_mov_b32_e32 v164, v82
	v_mov_b32_e32 v166, v83
	global_store_dwordx4 v[148:149], v[168:171], off nt
	s_cbranch_vccnz .LBB0_234
	v_mul_f32_e32 v162, 0xbfb8aa3b, v81
	v_mul_f32_e32 v163, 0xbfb8aa3b, v86
	v_exp_f32_e32 v162, v162
	v_exp_f32_e32 v164, v163
	v_mul_f32_e32 v163, 0xbfb8aa3b, v82
	v_exp_f32_e32 v165, v163
	v_add_f32_e32 v162, 1.0, v162
	v_mul_f32_e32 v150, 0xbfb8aa3b, v84
	v_mul_f32_e32 v151, 0xbfb8aa3b, v80
	v_mul_f32_e32 v161, 0xbfb8aa3b, v85
	v_rcp_f32_e32 v163, v162
	v_add_f32_e32 v162, 1.0, v164
	v_add_f32_e32 v164, 1.0, v165
	v_mul_f32_e32 v165, 0xbfb8aa3b, v87
	v_mul_f32_e32 v166, 0xbfb8aa3b, v83
	v_exp_f32_e32 v150, v150
	v_exp_f32_e32 v151, v151
	v_exp_f32_e32 v161, v161
	v_exp_f32_e32 v165, v165
	v_exp_f32_e32 v166, v166
	v_add_f32_e32 v150, 1.0, v150
	v_add_f32_e32 v151, 1.0, v151
	v_add_f32_e32 v161, 1.0, v161
	v_add_f32_e32 v165, 1.0, v165
	v_add_f32_e32 v166, 1.0, v166
	v_rcp_f32_e32 v150, v150
	v_rcp_f32_e32 v151, v151
	v_rcp_f32_e32 v161, v161
	v_rcp_f32_e32 v162, v162
	v_rcp_f32_e32 v164, v164
	v_rcp_f32_e32 v165, v165
	v_rcp_f32_e32 v166, v166
.LBB0_234:
	s_nop 0
	v_cvt_pk_bf16_f32 v168, v150, v161
	v_cvt_pk_bf16_f32 v169, v162, v165
	v_cvt_pk_bf16_f32 v170, v151, v163
	v_cvt_pk_bf16_f32 v171, v164, v166
	s_and_b64 vcc, exec, s[10:11]
	v_mov_b32_e32 v150, v76
	v_mov_b32_e32 v161, v77
	v_mov_b32_e32 v162, v78
	v_mov_b32_e32 v165, v79
	v_mov_b32_e32 v151, v72
	v_mov_b32_e32 v163, v73
	v_mov_b32_e32 v164, v74
	v_mov_b32_e32 v166, v75
	global_store_dwordx4 v[148:149], v[168:171], off offset:256 nt
	s_cbranch_vccnz .LBB0_236
	v_mul_f32_e32 v148, 0xbfb8aa3b, v76
	v_exp_f32_e32 v148, v148
	v_mul_f32_e32 v149, 0xbfb8aa3b, v72
	v_exp_f32_e32 v149, v149
	v_mul_f32_e32 v151, 0xbfb8aa3b, v73
	v_add_f32_e32 v148, 1.0, v148
	v_rcp_f32_e32 v150, v148
	v_mul_f32_e32 v148, 0xbfb8aa3b, v77
	v_exp_f32_e32 v148, v148
	v_exp_f32_e32 v162, v151
	v_add_f32_e32 v149, 1.0, v149
	v_rcp_f32_e32 v151, v149
	v_add_f32_e32 v148, 1.0, v148
	v_mul_f32_e32 v149, 0xbfb8aa3b, v78
	v_rcp_f32_e32 v161, v148
	v_add_f32_e32 v148, 1.0, v162
	v_exp_f32_e32 v149, v149
	v_mul_f32_e32 v162, 0xbfb8aa3b, v74
	v_exp_f32_e32 v164, v162
	v_rcp_f32_e32 v163, v148
	v_add_f32_e32 v148, 1.0, v149
	v_mul_f32_e32 v149, 0xbfb8aa3b, v79
	v_rcp_f32_e32 v162, v148
	v_add_f32_e32 v148, 1.0, v164
	v_exp_f32_e32 v149, v149
	v_mul_f32_e32 v164, 0xbfb8aa3b, v75
	v_exp_f32_e32 v166, v164
	v_rcp_f32_e32 v164, v148
	v_add_f32_e32 v148, 1.0, v149
	v_rcp_f32_e32 v165, v148
	v_add_f32_e32 v148, 1.0, v166
	v_rcp_f32_e32 v166, v148
.LBB0_236:
	v_readlane_b32 s2, v246, 26
	v_readlane_b32 s3, v246, 27
	v_or_b32_e32 v167, 48, v160
	v_cvt_pk_bf16_f32 v168, v150, v161
	v_cvt_pk_bf16_f32 v169, v162, v165
	v_cvt_pk_bf16_f32 v170, v151, v163
	v_cvt_pk_bf16_f32 v171, v164, v166
	s_nop 0
	v_mov_b64_e32 v[148:149], s[2:3]
	v_mad_i64_i32 v[148:149], s[2:3], v167, s51, v[148:149]
	v_lshl_add_u64 v[148:149], v[136:137], 1, v[148:149]
	s_and_b64 vcc, exec, s[10:11]
	v_mov_b32_e32 v150, v68
	v_mov_b32_e32 v161, v69
	v_mov_b32_e32 v162, v70
	v_mov_b32_e32 v165, v71
	v_mov_b32_e32 v151, v64
	v_mov_b32_e32 v163, v65
	v_mov_b32_e32 v164, v66
	v_mov_b32_e32 v166, v67
	global_store_dwordx4 v[148:149], v[168:171], off nt
	s_cbranch_vccnz .LBB0_238
	v_mul_f32_e32 v162, 0xbfb8aa3b, v65
	v_mul_f32_e32 v163, 0xbfb8aa3b, v70
	v_exp_f32_e32 v162, v162
	v_exp_f32_e32 v164, v163
	v_mul_f32_e32 v163, 0xbfb8aa3b, v66
	v_exp_f32_e32 v165, v163
	v_add_f32_e32 v162, 1.0, v162
	v_mul_f32_e32 v150, 0xbfb8aa3b, v68
	v_mul_f32_e32 v151, 0xbfb8aa3b, v64
	v_mul_f32_e32 v161, 0xbfb8aa3b, v69
	v_rcp_f32_e32 v163, v162
	v_add_f32_e32 v162, 1.0, v164
	v_add_f32_e32 v164, 1.0, v165
	v_mul_f32_e32 v165, 0xbfb8aa3b, v71
	v_mul_f32_e32 v166, 0xbfb8aa3b, v67
	v_exp_f32_e32 v150, v150
	v_exp_f32_e32 v151, v151
	v_exp_f32_e32 v161, v161
	v_exp_f32_e32 v165, v165
	v_exp_f32_e32 v166, v166
	v_add_f32_e32 v150, 1.0, v150
	v_add_f32_e32 v151, 1.0, v151
	v_add_f32_e32 v161, 1.0, v161
	v_add_f32_e32 v165, 1.0, v165
	v_add_f32_e32 v166, 1.0, v166
	v_rcp_f32_e32 v150, v150
	v_rcp_f32_e32 v151, v151
	v_rcp_f32_e32 v161, v161
	v_rcp_f32_e32 v162, v162
	v_rcp_f32_e32 v164, v164
	v_rcp_f32_e32 v165, v165
	v_rcp_f32_e32 v166, v166
.LBB0_238:
	s_nop 0
	v_cvt_pk_bf16_f32 v168, v150, v161
	v_cvt_pk_bf16_f32 v169, v162, v165
	v_cvt_pk_bf16_f32 v170, v151, v163
	v_cvt_pk_bf16_f32 v171, v164, v166
	s_and_b64 vcc, exec, s[10:11]
	v_mov_b32_e32 v150, v60
	v_mov_b32_e32 v161, v61
	v_mov_b32_e32 v162, v62
	v_mov_b32_e32 v165, v63
	v_mov_b32_e32 v151, v56
	v_mov_b32_e32 v163, v57
	v_mov_b32_e32 v164, v58
	v_mov_b32_e32 v166, v59
	global_store_dwordx4 v[148:149], v[168:171], off offset:256 nt
	s_cbranch_vccnz .LBB0_240
	v_mul_f32_e32 v148, 0xbfb8aa3b, v60
	v_exp_f32_e32 v148, v148
	v_mul_f32_e32 v149, 0xbfb8aa3b, v56
	v_exp_f32_e32 v149, v149
	v_mul_f32_e32 v151, 0xbfb8aa3b, v57
	v_add_f32_e32 v148, 1.0, v148
	v_rcp_f32_e32 v150, v148
	v_mul_f32_e32 v148, 0xbfb8aa3b, v61
	v_exp_f32_e32 v148, v148
	v_exp_f32_e32 v162, v151
	v_add_f32_e32 v149, 1.0, v149
	v_rcp_f32_e32 v151, v149
	v_add_f32_e32 v148, 1.0, v148
	v_mul_f32_e32 v149, 0xbfb8aa3b, v62
	v_rcp_f32_e32 v161, v148
	v_add_f32_e32 v148, 1.0, v162
	v_exp_f32_e32 v149, v149
	v_mul_f32_e32 v162, 0xbfb8aa3b, v58
	v_exp_f32_e32 v164, v162
	v_rcp_f32_e32 v163, v148
	v_add_f32_e32 v148, 1.0, v149
	v_mul_f32_e32 v149, 0xbfb8aa3b, v63
	v_rcp_f32_e32 v162, v148
	v_add_f32_e32 v148, 1.0, v164
	v_exp_f32_e32 v149, v149
	v_mul_f32_e32 v164, 0xbfb8aa3b, v59
	v_exp_f32_e32 v166, v164
	v_rcp_f32_e32 v164, v148
	v_add_f32_e32 v148, 1.0, v149
	v_rcp_f32_e32 v165, v148
	v_add_f32_e32 v148, 1.0, v166
	v_rcp_f32_e32 v166, v148
.LBB0_240:
	v_readlane_b32 s2, v246, 26
	v_readlane_b32 s3, v246, 27
	v_add_u32_e32 v167, 0x80, v160
	v_cvt_pk_bf16_f32 v168, v150, v161
	v_cvt_pk_bf16_f32 v169, v162, v165
	v_cvt_pk_bf16_f32 v170, v151, v163
	v_cvt_pk_bf16_f32 v171, v164, v166
	s_nop 0
	v_mov_b64_e32 v[148:149], s[2:3]
	v_mad_i64_i32 v[148:149], s[2:3], v167, s51, v[148:149]
	v_lshl_add_u64 v[148:149], v[136:137], 1, v[148:149]
	s_and_b64 vcc, exec, s[10:11]
	v_mov_b32_e32 v150, v52
	v_mov_b32_e32 v161, v53
	v_mov_b32_e32 v162, v54
	v_mov_b32_e32 v165, v55
	v_mov_b32_e32 v151, v48
	v_mov_b32_e32 v163, v49
	v_mov_b32_e32 v164, v50
	v_mov_b32_e32 v166, v51
	global_store_dwordx4 v[148:149], v[168:171], off nt
	s_cbranch_vccnz .LBB0_242
	v_mul_f32_e32 v162, 0xbfb8aa3b, v49
	v_mul_f32_e32 v163, 0xbfb8aa3b, v54
	v_exp_f32_e32 v162, v162
	v_exp_f32_e32 v164, v163
	v_mul_f32_e32 v163, 0xbfb8aa3b, v50
	v_exp_f32_e32 v165, v163
	v_add_f32_e32 v162, 1.0, v162
	v_mul_f32_e32 v150, 0xbfb8aa3b, v52
	v_mul_f32_e32 v151, 0xbfb8aa3b, v48
	v_mul_f32_e32 v161, 0xbfb8aa3b, v53
	v_rcp_f32_e32 v163, v162
	v_add_f32_e32 v162, 1.0, v164
	v_add_f32_e32 v164, 1.0, v165
	v_mul_f32_e32 v165, 0xbfb8aa3b, v55
	v_mul_f32_e32 v166, 0xbfb8aa3b, v51
	v_exp_f32_e32 v150, v150
	v_exp_f32_e32 v151, v151
	v_exp_f32_e32 v161, v161
	v_exp_f32_e32 v165, v165
	v_exp_f32_e32 v166, v166
	v_add_f32_e32 v150, 1.0, v150
	v_add_f32_e32 v151, 1.0, v151
	v_add_f32_e32 v161, 1.0, v161
	v_add_f32_e32 v165, 1.0, v165
	v_add_f32_e32 v166, 1.0, v166
	v_rcp_f32_e32 v150, v150
	v_rcp_f32_e32 v151, v151
	v_rcp_f32_e32 v161, v161
	v_rcp_f32_e32 v162, v162
	v_rcp_f32_e32 v164, v164
	v_rcp_f32_e32 v165, v165
	v_rcp_f32_e32 v166, v166
.LBB0_242:
	s_nop 0
	v_cvt_pk_bf16_f32 v168, v150, v161
	v_cvt_pk_bf16_f32 v169, v162, v165
	v_cvt_pk_bf16_f32 v170, v151, v163
	v_cvt_pk_bf16_f32 v171, v164, v166
	s_and_b64 vcc, exec, s[10:11]
	v_mov_b32_e32 v150, v44
	v_mov_b32_e32 v161, v45
	v_mov_b32_e32 v162, v46
	v_mov_b32_e32 v165, v47
	v_mov_b32_e32 v151, v40
	v_mov_b32_e32 v163, v41
	v_mov_b32_e32 v164, v42
	v_mov_b32_e32 v166, v43
	global_store_dwordx4 v[148:149], v[168:171], off offset:256 nt
	s_cbranch_vccnz .LBB0_244
	v_mul_f32_e32 v148, 0xbfb8aa3b, v44
	v_exp_f32_e32 v148, v148
	v_mul_f32_e32 v149, 0xbfb8aa3b, v40
	v_exp_f32_e32 v149, v149
	v_mul_f32_e32 v151, 0xbfb8aa3b, v41
	v_add_f32_e32 v148, 1.0, v148
	v_rcp_f32_e32 v150, v148
	v_mul_f32_e32 v148, 0xbfb8aa3b, v45
	v_exp_f32_e32 v148, v148
	v_exp_f32_e32 v162, v151
	v_add_f32_e32 v149, 1.0, v149
	v_rcp_f32_e32 v151, v149
	v_add_f32_e32 v148, 1.0, v148
	v_mul_f32_e32 v149, 0xbfb8aa3b, v46
	v_rcp_f32_e32 v161, v148
	v_add_f32_e32 v148, 1.0, v162
	v_exp_f32_e32 v149, v149
	v_mul_f32_e32 v162, 0xbfb8aa3b, v42
	v_exp_f32_e32 v164, v162
	v_rcp_f32_e32 v163, v148
	v_add_f32_e32 v148, 1.0, v149
	v_mul_f32_e32 v149, 0xbfb8aa3b, v47
	v_rcp_f32_e32 v162, v148
	v_add_f32_e32 v148, 1.0, v164
	v_exp_f32_e32 v149, v149
	v_mul_f32_e32 v164, 0xbfb8aa3b, v43
	v_exp_f32_e32 v166, v164
	v_rcp_f32_e32 v164, v148
	v_add_f32_e32 v148, 1.0, v149
	v_rcp_f32_e32 v165, v148
	v_add_f32_e32 v148, 1.0, v166
	v_rcp_f32_e32 v166, v148
.LBB0_244:
	v_readlane_b32 s2, v246, 26
	v_readlane_b32 s3, v246, 27
	v_add_u32_e32 v167, 0x90, v160
	v_cvt_pk_bf16_f32 v168, v150, v161
	v_cvt_pk_bf16_f32 v169, v162, v165
	v_cvt_pk_bf16_f32 v170, v151, v163
	v_cvt_pk_bf16_f32 v171, v164, v166
	s_nop 0
	v_mov_b64_e32 v[148:149], s[2:3]
	v_mad_i64_i32 v[148:149], s[2:3], v167, s51, v[148:149]
	v_lshl_add_u64 v[148:149], v[136:137], 1, v[148:149]
	s_and_b64 vcc, exec, s[10:11]
	v_mov_b32_e32 v150, v36
	v_mov_b32_e32 v161, v37
	v_mov_b32_e32 v162, v38
	v_mov_b32_e32 v165, v39
	v_mov_b32_e32 v151, v32
	v_mov_b32_e32 v163, v33
	v_mov_b32_e32 v164, v34
	v_mov_b32_e32 v166, v35
	global_store_dwordx4 v[148:149], v[168:171], off nt
	s_cbranch_vccnz .LBB0_246
	v_mul_f32_e32 v162, 0xbfb8aa3b, v33
	v_mul_f32_e32 v163, 0xbfb8aa3b, v38
	v_exp_f32_e32 v162, v162
	v_exp_f32_e32 v164, v163
	v_mul_f32_e32 v163, 0xbfb8aa3b, v34
	v_exp_f32_e32 v165, v163
	v_add_f32_e32 v162, 1.0, v162
	v_mul_f32_e32 v150, 0xbfb8aa3b, v36
	v_mul_f32_e32 v151, 0xbfb8aa3b, v32
	v_mul_f32_e32 v161, 0xbfb8aa3b, v37
	v_rcp_f32_e32 v163, v162
	v_add_f32_e32 v162, 1.0, v164
	v_add_f32_e32 v164, 1.0, v165
	v_mul_f32_e32 v165, 0xbfb8aa3b, v39
	v_mul_f32_e32 v166, 0xbfb8aa3b, v35
	v_exp_f32_e32 v150, v150
	v_exp_f32_e32 v151, v151
	v_exp_f32_e32 v161, v161
	v_exp_f32_e32 v165, v165
	v_exp_f32_e32 v166, v166
	v_add_f32_e32 v150, 1.0, v150
	v_add_f32_e32 v151, 1.0, v151
	v_add_f32_e32 v161, 1.0, v161
	v_add_f32_e32 v165, 1.0, v165
	v_add_f32_e32 v166, 1.0, v166
	v_rcp_f32_e32 v150, v150
	v_rcp_f32_e32 v151, v151
	v_rcp_f32_e32 v161, v161
	v_rcp_f32_e32 v162, v162
	v_rcp_f32_e32 v164, v164
	v_rcp_f32_e32 v165, v165
	v_rcp_f32_e32 v166, v166
.LBB0_246:
	s_nop 0
	v_cvt_pk_bf16_f32 v168, v150, v161
	v_cvt_pk_bf16_f32 v169, v162, v165
	v_cvt_pk_bf16_f32 v170, v151, v163
	v_cvt_pk_bf16_f32 v171, v164, v166
	s_and_b64 vcc, exec, s[10:11]
	v_mov_b32_e32 v150, v28
	v_mov_b32_e32 v161, v29
	v_mov_b32_e32 v162, v30
	v_mov_b32_e32 v165, v31
	v_mov_b32_e32 v151, v24
	v_mov_b32_e32 v163, v25
	v_mov_b32_e32 v164, v26
	v_mov_b32_e32 v166, v27
	global_store_dwordx4 v[148:149], v[168:171], off offset:256 nt
	s_cbranch_vccnz .LBB0_248
	v_mul_f32_e32 v148, 0xbfb8aa3b, v28
	v_exp_f32_e32 v148, v148
	v_mul_f32_e32 v149, 0xbfb8aa3b, v24
	v_exp_f32_e32 v149, v149
	v_mul_f32_e32 v151, 0xbfb8aa3b, v25
	v_add_f32_e32 v148, 1.0, v148
	v_rcp_f32_e32 v150, v148
	v_mul_f32_e32 v148, 0xbfb8aa3b, v29
	v_exp_f32_e32 v148, v148
	v_exp_f32_e32 v162, v151
	v_add_f32_e32 v149, 1.0, v149
	v_rcp_f32_e32 v151, v149
	v_add_f32_e32 v148, 1.0, v148
	v_mul_f32_e32 v149, 0xbfb8aa3b, v30
	v_rcp_f32_e32 v161, v148
	v_add_f32_e32 v148, 1.0, v162
	v_exp_f32_e32 v149, v149
	v_mul_f32_e32 v162, 0xbfb8aa3b, v26
	v_exp_f32_e32 v164, v162
	v_rcp_f32_e32 v163, v148
	v_add_f32_e32 v148, 1.0, v149
	v_mul_f32_e32 v149, 0xbfb8aa3b, v31
	v_rcp_f32_e32 v162, v148
	v_add_f32_e32 v148, 1.0, v164
	v_exp_f32_e32 v149, v149
	v_mul_f32_e32 v164, 0xbfb8aa3b, v27
	v_exp_f32_e32 v166, v164
	v_rcp_f32_e32 v164, v148
	v_add_f32_e32 v148, 1.0, v149
	v_rcp_f32_e32 v165, v148
	v_add_f32_e32 v148, 1.0, v166
	v_rcp_f32_e32 v166, v148
.LBB0_248:
	v_readlane_b32 s2, v246, 26
	v_readlane_b32 s3, v246, 27
	v_add_u32_e32 v167, 0xa0, v160
	v_cvt_pk_bf16_f32 v168, v150, v161
	v_cvt_pk_bf16_f32 v169, v162, v165
	v_cvt_pk_bf16_f32 v170, v151, v163
	v_cvt_pk_bf16_f32 v171, v164, v166
	s_nop 0
	v_mov_b64_e32 v[148:149], s[2:3]
	v_mad_i64_i32 v[148:149], s[2:3], v167, s51, v[148:149]
	v_lshl_add_u64 v[148:149], v[136:137], 1, v[148:149]
	s_and_b64 vcc, exec, s[10:11]
	v_mov_b32_e32 v150, v20
	v_mov_b32_e32 v161, v21
	v_mov_b32_e32 v162, v22
	v_mov_b32_e32 v165, v23
	v_mov_b32_e32 v151, v16
	v_mov_b32_e32 v163, v17
	v_mov_b32_e32 v164, v18
	v_mov_b32_e32 v166, v19
	global_store_dwordx4 v[148:149], v[168:171], off nt
	s_cbranch_vccnz .LBB0_250
	v_mul_f32_e32 v162, 0xbfb8aa3b, v17
	v_mul_f32_e32 v163, 0xbfb8aa3b, v22
	v_exp_f32_e32 v162, v162
	v_exp_f32_e32 v164, v163
	v_mul_f32_e32 v163, 0xbfb8aa3b, v18
	v_exp_f32_e32 v165, v163
	v_add_f32_e32 v162, 1.0, v162
	v_mul_f32_e32 v150, 0xbfb8aa3b, v20
	v_mul_f32_e32 v151, 0xbfb8aa3b, v16
	v_mul_f32_e32 v161, 0xbfb8aa3b, v21
	v_rcp_f32_e32 v163, v162
	v_add_f32_e32 v162, 1.0, v164
	v_add_f32_e32 v164, 1.0, v165
	v_mul_f32_e32 v165, 0xbfb8aa3b, v23
	v_mul_f32_e32 v166, 0xbfb8aa3b, v19
	v_exp_f32_e32 v150, v150
	v_exp_f32_e32 v151, v151
	v_exp_f32_e32 v161, v161
	v_exp_f32_e32 v165, v165
	v_exp_f32_e32 v166, v166
	v_add_f32_e32 v150, 1.0, v150
	v_add_f32_e32 v151, 1.0, v151
	v_add_f32_e32 v161, 1.0, v161
	v_add_f32_e32 v165, 1.0, v165
	v_add_f32_e32 v166, 1.0, v166
	v_rcp_f32_e32 v150, v150
	v_rcp_f32_e32 v151, v151
	v_rcp_f32_e32 v161, v161
	v_rcp_f32_e32 v162, v162
	v_rcp_f32_e32 v164, v164
	v_rcp_f32_e32 v165, v165
	v_rcp_f32_e32 v166, v166
.LBB0_250:
	s_nop 0
	v_cvt_pk_bf16_f32 v168, v150, v161
	v_cvt_pk_bf16_f32 v169, v162, v165
	v_cvt_pk_bf16_f32 v170, v151, v163
	v_cvt_pk_bf16_f32 v171, v164, v166
	s_and_b64 vcc, exec, s[10:11]
	v_mov_b32_e32 v150, v12
	v_mov_b32_e32 v161, v13
	v_mov_b32_e32 v162, v14
	v_mov_b32_e32 v165, v15
	v_mov_b32_e32 v151, v8
	v_mov_b32_e32 v163, v9
	v_mov_b32_e32 v164, v10
	v_mov_b32_e32 v166, v11
	global_store_dwordx4 v[148:149], v[168:171], off offset:256 nt
	s_cbranch_vccnz .LBB0_252
	v_mul_f32_e32 v148, 0xbfb8aa3b, v12
	v_exp_f32_e32 v148, v148
	v_mul_f32_e32 v149, 0xbfb8aa3b, v8
	v_exp_f32_e32 v149, v149
	v_mul_f32_e32 v151, 0xbfb8aa3b, v9
	v_add_f32_e32 v148, 1.0, v148
	v_rcp_f32_e32 v150, v148
	v_mul_f32_e32 v148, 0xbfb8aa3b, v13
	v_exp_f32_e32 v148, v148
	v_exp_f32_e32 v162, v151
	v_add_f32_e32 v149, 1.0, v149
	v_rcp_f32_e32 v151, v149
	v_add_f32_e32 v148, 1.0, v148
	v_mul_f32_e32 v149, 0xbfb8aa3b, v14
	v_rcp_f32_e32 v161, v148
	v_add_f32_e32 v148, 1.0, v162
	v_exp_f32_e32 v149, v149
	v_mul_f32_e32 v162, 0xbfb8aa3b, v10
	v_exp_f32_e32 v164, v162
	v_rcp_f32_e32 v163, v148
	v_add_f32_e32 v148, 1.0, v149
	v_mul_f32_e32 v149, 0xbfb8aa3b, v15
	v_rcp_f32_e32 v162, v148
	v_add_f32_e32 v148, 1.0, v164
	v_exp_f32_e32 v149, v149
	v_mul_f32_e32 v164, 0xbfb8aa3b, v11
	v_exp_f32_e32 v166, v164
	v_rcp_f32_e32 v164, v148
	v_add_f32_e32 v148, 1.0, v149
	v_rcp_f32_e32 v165, v148
	v_add_f32_e32 v148, 1.0, v166
	v_rcp_f32_e32 v166, v148
.LBB0_252:
	v_readlane_b32 s2, v246, 26
	v_readlane_b32 s3, v246, 27
	v_add_u32_e32 v167, 0xb0, v160
	v_cvt_pk_bf16_f32 v168, v150, v161
	v_cvt_pk_bf16_f32 v169, v162, v165
	v_cvt_pk_bf16_f32 v170, v151, v163
	v_cvt_pk_bf16_f32 v171, v164, v166
	s_nop 0
	v_mov_b64_e32 v[148:149], s[2:3]
	v_mad_i64_i32 v[148:149], s[2:3], v167, s51, v[148:149]
	v_lshl_add_u64 v[148:149], v[136:137], 1, v[148:149]
	s_and_b64 vcc, exec, s[10:11]
	v_mov_b32_e32 v150, v4
	v_mov_b32_e32 v161, v5
	v_mov_b32_e32 v163, v6
	v_mov_b32_e32 v166, v7
	v_mov_b32_e32 v151, v0
	v_mov_b32_e32 v162, v1
	v_mov_b32_e32 v164, v2
	v_mov_b32_e32 v165, v3
	global_store_dwordx4 v[148:149], v[168:171], off nt
	s_cbranch_vccnz .LBB0_254
	v_mul_f32_e32 v165, 0xbfb8aa3b, v7
	v_mul_f32_e32 v150, 0xbfb8aa3b, v4
	v_mul_f32_e32 v151, 0xbfb8aa3b, v0
	v_mul_f32_e32 v161, 0xbfb8aa3b, v5
	v_mul_f32_e32 v162, 0xbfb8aa3b, v1
	v_mul_f32_e32 v163, 0xbfb8aa3b, v6
	v_mul_f32_e32 v164, 0xbfb8aa3b, v2
	v_exp_f32_e32 v165, v165
	v_mul_f32_e32 v166, 0xbfb8aa3b, v3
	v_exp_f32_e32 v150, v150
	v_exp_f32_e32 v151, v151
	v_exp_f32_e32 v161, v161
	v_exp_f32_e32 v162, v162
	v_exp_f32_e32 v163, v163
	v_exp_f32_e32 v164, v164
	v_exp_f32_e32 v167, v166
	v_add_f32_e32 v165, 1.0, v165
	v_add_f32_e32 v150, 1.0, v150
	v_add_f32_e32 v151, 1.0, v151
	v_add_f32_e32 v161, 1.0, v161
	v_add_f32_e32 v162, 1.0, v162
	v_add_f32_e32 v163, 1.0, v163
	v_add_f32_e32 v164, 1.0, v164
	v_rcp_f32_e32 v166, v165
	v_add_f32_e32 v165, 1.0, v167
	v_rcp_f32_e32 v150, v150
	v_rcp_f32_e32 v151, v151
	v_rcp_f32_e32 v161, v161
	v_rcp_f32_e32 v162, v162
	v_rcp_f32_e32 v163, v163
	v_rcp_f32_e32 v164, v164
	v_rcp_f32_e32 v165, v165
.LBB0_254:
	s_nop 0
	v_cvt_pk_bf16_f32 v168, v150, v161
	v_cvt_pk_bf16_f32 v169, v163, v166
	v_cvt_pk_bf16_f32 v170, v151, v162
	v_cvt_pk_bf16_f32 v171, v164, v165
	global_store_dwordx4 v[148:149], v[168:171], off offset:256 nt

.LBB0_256:
	s_andn2_b64 vcc, exec, s[2:3]
	s_cbranch_vccnz .LBB0_291
	v_lshlrev_b32_e32 v148, 3, v160
	v_and_or_b32 v148, v148, s53, v155
	v_lshlrev_b32_e32 v148, 5, v148
	global_load_dwordx4 v[162:165], v148, s[14:15] offset:16
	global_load_dwordx4 v[166:169], v148, s[14:15]
	v_readlane_b32 s2, v246, 26
	s_cmp_gt_i32 s4, 1
	v_readlane_b32 s3, v246, 27
	v_or_b32_e32 v161, 16, v160
	v_ashrrev_i32_e32 v151, 31, v136
	v_mov_b64_e32 v[148:149], s[2:3]
	s_cselect_b64 s[2:3], -1, 0
	v_mov_b32_e32 v150, v136
	v_cndmask_b32_e64 v136, v159, 1.0, s[2:3]
	v_lshlrev_b32_e32 v180, 3, v161
	v_pk_mul_f32 v[126:127], v[136:137], v[126:127] op_sel_hi:[0,1]
	v_pk_mul_f32 v[172:173], v[136:137], v[124:125] op_sel_hi:[0,1]
	v_pk_mul_f32 v[122:123], v[136:137], v[122:123] op_sel_hi:[0,1]
	v_pk_mul_f32 v[174:175], v[136:137], v[120:121] op_sel_hi:[0,1]
	v_pk_mul_f32 v[118:119], v[136:137], v[118:119] op_sel_hi:[0,1]
	v_pk_mul_f32 v[176:177], v[136:137], v[116:117] op_sel_hi:[0,1]
	v_pk_mul_f32 v[114:115], v[136:137], v[114:115] op_sel_hi:[0,1]
	v_pk_mul_f32 v[178:179], v[136:137], v[112:113] op_sel_hi:[0,1]
	v_and_or_b32 v112, v180, s54, v155
	v_mad_i64_i32 v[170:171], s[2:3], v160, s51, v[148:149]
	v_lshlrev_b64 v[150:151], 1, v[150:151]
	v_lshlrev_b32_e32 v186, 5, v112
	v_lshl_add_u64 v[170:171], v[170:171], 0, v[150:151]
	v_pk_mul_f32 v[110:111], v[136:137], v[110:111] op_sel_hi:[0,1]
	v_pk_mul_f32 v[106:107], v[136:137], v[106:107] op_sel_hi:[0,1]
	v_pk_mul_f32 v[102:103], v[136:137], v[102:103] op_sel_hi:[0,1]
	v_pk_mul_f32 v[98:99], v[136:137], v[98:99] op_sel_hi:[0,1]
	v_pk_mul_f32 v[94:95], v[136:137], v[94:95] op_sel_hi:[0,1]
	v_pk_mul_f32 v[90:91], v[136:137], v[90:91] op_sel_hi:[0,1]
	v_pk_mul_f32 v[86:87], v[136:137], v[86:87] op_sel_hi:[0,1]
	v_pk_mul_f32 v[82:83], v[136:137], v[82:83] op_sel_hi:[0,1]
	v_pk_mul_f32 v[78:79], v[136:137], v[78:79] op_sel_hi:[0,1]
	v_pk_mul_f32 v[74:75], v[136:137], v[74:75] op_sel_hi:[0,1]
	v_pk_mul_f32 v[70:71], v[136:137], v[70:71] op_sel_hi:[0,1]
	v_pk_mul_f32 v[66:67], v[136:137], v[66:67] op_sel_hi:[0,1]
	v_pk_mul_f32 v[62:63], v[136:137], v[62:63] op_sel_hi:[0,1]
	v_pk_mul_f32 v[58:59], v[136:137], v[58:59] op_sel_hi:[0,1]
	v_pk_mul_f32 v[54:55], v[136:137], v[54:55] op_sel_hi:[0,1]
	v_pk_mul_f32 v[50:51], v[136:137], v[50:51] op_sel_hi:[0,1]
	v_pk_mul_f32 v[46:47], v[136:137], v[46:47] op_sel_hi:[0,1]
	v_pk_mul_f32 v[42:43], v[136:137], v[42:43] op_sel_hi:[0,1]
	v_pk_mul_f32 v[38:39], v[136:137], v[38:39] op_sel_hi:[0,1]
	v_pk_mul_f32 v[34:35], v[136:137], v[34:35] op_sel_hi:[0,1]
	v_pk_mul_f32 v[30:31], v[136:137], v[30:31] op_sel_hi:[0,1]
	v_pk_mul_f32 v[26:27], v[136:137], v[26:27] op_sel_hi:[0,1]
	v_pk_mul_f32 v[22:23], v[136:137], v[22:23] op_sel_hi:[0,1]
	v_pk_mul_f32 v[18:19], v[136:137], v[18:19] op_sel_hi:[0,1]
	v_pk_mul_f32 v[14:15], v[136:137], v[14:15] op_sel_hi:[0,1]
	v_pk_mul_f32 v[10:11], v[136:137], v[10:11] op_sel_hi:[0,1]
	v_pk_mul_f32 v[6:7], v[136:137], v[6:7] op_sel_hi:[0,1]
	v_pk_mul_f32 v[2:3], v[136:137], v[2:3] op_sel_hi:[0,1]
	s_cmp_lt_i32 s4, 2
	s_waitcnt vmcnt(0)
	v_pk_mul_f32 v[112:113], v[122:123], v[164:165]
	v_pk_mul_f32 v[116:117], v[174:175], v[162:163]
	v_pk_mul_f32 v[120:121], v[126:127], v[164:165]
	v_pk_mul_f32 v[180:181], v[172:173], v[162:163]
	v_pk_mul_f32 v[182:183], v[114:115], v[164:165]
	v_pk_mul_f32 v[184:185], v[178:179], v[162:163]
	v_pk_mul_f32 v[164:165], v[118:119], v[164:165]
	v_pk_mul_f32 v[162:163], v[176:177], v[162:163]
	v_pk_fma_f32 v[124:125], v[126:127], v[168:169], v[112:113] neg_lo:[0,0,1] neg_hi:[0,0,1]
	v_pk_fma_f32 v[126:127], v[172:173], v[166:167], v[116:117] neg_lo:[0,0,1] neg_hi:[0,0,1]
	v_pk_fma_f32 v[120:121], v[122:123], v[168:169], v[120:121]
	v_pk_fma_f32 v[122:123], v[174:175], v[166:167], v[180:181]
	v_pk_fma_f32 v[112:113], v[114:115], v[168:169], v[164:165]
	v_pk_fma_f32 v[114:115], v[178:179], v[166:167], v[162:163]
	v_cvt_pk_bf16_f32 v162, v126, v127
	v_cvt_pk_bf16_f32 v163, v124, v125
	v_cvt_pk_bf16_f32 v164, v122, v123
	v_cvt_pk_bf16_f32 v165, v120, v121
	v_pk_fma_f32 v[116:117], v[118:119], v[168:169], v[182:183] neg_lo:[0,0,1] neg_hi:[0,0,1]
	v_pk_fma_f32 v[118:119], v[176:177], v[166:167], v[184:185] neg_lo:[0,0,1] neg_hi:[0,0,1]
	global_store_dwordx4 v[170:171], v[162:165], off nt
	v_pk_mul_f32 v[172:173], v[136:137], v[108:109] op_sel_hi:[0,1]
	v_pk_mul_f32 v[174:175], v[136:137], v[104:105] op_sel_hi:[0,1]
	v_cvt_pk_bf16_f32 v162, v118, v119
	v_cvt_pk_bf16_f32 v163, v116, v117
	v_cvt_pk_bf16_f32 v164, v114, v115
	v_cvt_pk_bf16_f32 v165, v112, v113
	global_store_dwordx4 v[170:171], v[162:165], off offset:256 nt
	global_load_dwordx4 v[162:165], v186, s[14:15] offset:16
	s_nop 0
	global_load_dwordx4 v[166:169], v186, s[14:15]
	v_or_b32_e32 v186, 32, v160
	v_mad_i64_i32 v[170:171], s[2:3], v161, s51, v[148:149]
	v_lshlrev_b32_e32 v161, 3, v186
	v_pk_mul_f32 v[176:177], v[136:137], v[100:101] op_sel_hi:[0,1]
	v_pk_mul_f32 v[178:179], v[136:137], v[96:97] op_sel_hi:[0,1]
	v_and_or_b32 v96, v161, s55, v155
	v_lshlrev_b32_e32 v161, 5, v96
	v_lshl_add_u64 v[170:171], v[170:171], 0, v[150:151]
	s_waitcnt vmcnt(1)
	v_pk_mul_f32 v[96:97], v[106:107], v[164:165]
	v_pk_mul_f32 v[100:101], v[174:175], v[162:163]
	v_pk_mul_f32 v[104:105], v[110:111], v[164:165]
	v_pk_mul_f32 v[180:181], v[172:173], v[162:163]
	v_pk_mul_f32 v[182:183], v[98:99], v[164:165]
	v_pk_mul_f32 v[184:185], v[178:179], v[162:163]
	v_pk_mul_f32 v[164:165], v[102:103], v[164:165]
	v_pk_mul_f32 v[162:163], v[176:177], v[162:163]
	s_waitcnt vmcnt(0)
	v_pk_fma_f32 v[108:109], v[110:111], v[168:169], v[96:97] neg_lo:[0,0,1] neg_hi:[0,0,1]
	v_pk_fma_f32 v[110:111], v[172:173], v[166:167], v[100:101] neg_lo:[0,0,1] neg_hi:[0,0,1]
	v_pk_fma_f32 v[104:105], v[106:107], v[168:169], v[104:105]
	v_pk_fma_f32 v[106:107], v[174:175], v[166:167], v[180:181]
	v_pk_fma_f32 v[96:97], v[98:99], v[168:169], v[164:165]
	v_pk_fma_f32 v[98:99], v[178:179], v[166:167], v[162:163]
	v_cvt_pk_bf16_f32 v162, v110, v111
	v_cvt_pk_bf16_f32 v163, v108, v109
	v_cvt_pk_bf16_f32 v164, v106, v107
	v_cvt_pk_bf16_f32 v165, v104, v105
	v_pk_fma_f32 v[100:101], v[102:103], v[168:169], v[182:183] neg_lo:[0,0,1] neg_hi:[0,0,1]
	v_pk_fma_f32 v[102:103], v[176:177], v[166:167], v[184:185] neg_lo:[0,0,1] neg_hi:[0,0,1]
	global_store_dwordx4 v[170:171], v[162:165], off nt
	v_pk_mul_f32 v[172:173], v[136:137], v[92:93] op_sel_hi:[0,1]
	v_pk_mul_f32 v[174:175], v[136:137], v[88:89] op_sel_hi:[0,1]
	v_cvt_pk_bf16_f32 v162, v102, v103
	v_cvt_pk_bf16_f32 v163, v100, v101
	v_cvt_pk_bf16_f32 v164, v98, v99
	v_cvt_pk_bf16_f32 v165, v96, v97
	global_store_dwordx4 v[170:171], v[162:165], off offset:256 nt
	global_load_dwordx4 v[162:165], v161, s[14:15] offset:16
	s_nop 0
	global_load_dwordx4 v[166:169], v161, s[14:15]
	v_or_b32_e32 v161, 48, v160
	v_lshlrev_b32_e32 v180, 3, v161
	v_pk_mul_f32 v[176:177], v[136:137], v[84:85] op_sel_hi:[0,1]
	v_pk_mul_f32 v[178:179], v[136:137], v[80:81] op_sel_hi:[0,1]
	v_and_or_b32 v80, v180, s56, v155
	v_mad_i64_i32 v[170:171], s[2:3], v186, s51, v[148:149]
	v_lshlrev_b32_e32 v186, 5, v80
	v_lshl_add_u64 v[170:171], v[170:171], 0, v[150:151]
	s_waitcnt vmcnt(1)
	v_pk_mul_f32 v[80:81], v[90:91], v[164:165]
	v_pk_mul_f32 v[84:85], v[174:175], v[162:163]
	v_pk_mul_f32 v[88:89], v[94:95], v[164:165]
	v_pk_mul_f32 v[180:181], v[172:173], v[162:163]
	v_pk_mul_f32 v[182:183], v[82:83], v[164:165]
	v_pk_mul_f32 v[184:185], v[178:179], v[162:163]
	v_pk_mul_f32 v[164:165], v[86:87], v[164:165]
	v_pk_mul_f32 v[162:163], v[176:177], v[162:163]
	s_waitcnt vmcnt(0)
	v_pk_fma_f32 v[92:93], v[94:95], v[168:169], v[80:81] neg_lo:[0,0,1] neg_hi:[0,0,1]
	v_pk_fma_f32 v[94:95], v[172:173], v[166:167], v[84:85] neg_lo:[0,0,1] neg_hi:[0,0,1]
	v_pk_fma_f32 v[88:89], v[90:91], v[168:169], v[88:89]
	v_pk_fma_f32 v[90:91], v[174:175], v[166:167], v[180:181]
	v_pk_fma_f32 v[80:81], v[82:83], v[168:169], v[164:165]
	v_pk_fma_f32 v[82:83], v[178:179], v[166:167], v[162:163]
	v_cvt_pk_bf16_f32 v162, v94, v95
	v_cvt_pk_bf16_f32 v163, v92, v93
	v_cvt_pk_bf16_f32 v164, v90, v91
	v_cvt_pk_bf16_f32 v165, v88, v89
	v_pk_fma_f32 v[84:85], v[86:87], v[168:169], v[182:183] neg_lo:[0,0,1] neg_hi:[0,0,1]
	v_pk_fma_f32 v[86:87], v[176:177], v[166:167], v[184:185] neg_lo:[0,0,1] neg_hi:[0,0,1]
	global_store_dwordx4 v[170:171], v[162:165], off nt
	v_pk_mul_f32 v[172:173], v[136:137], v[76:77] op_sel_hi:[0,1]
	v_pk_mul_f32 v[174:175], v[136:137], v[72:73] op_sel_hi:[0,1]
	v_cvt_pk_bf16_f32 v162, v86, v87
	v_cvt_pk_bf16_f32 v163, v84, v85
	v_cvt_pk_bf16_f32 v164, v82, v83
	v_cvt_pk_bf16_f32 v165, v80, v81
	global_store_dwordx4 v[170:171], v[162:165], off offset:256 nt
	global_load_dwordx4 v[162:165], v186, s[14:15] offset:16
	s_nop 0
	global_load_dwordx4 v[166:169], v186, s[14:15]
	v_add_u32_e32 v186, 0x80, v160
	v_mad_i64_i32 v[170:171], s[2:3], v161, s51, v[148:149]
	v_lshlrev_b32_e32 v161, 3, v186
	v_pk_mul_f32 v[176:177], v[136:137], v[68:69] op_sel_hi:[0,1]
	v_pk_mul_f32 v[178:179], v[136:137], v[64:65] op_sel_hi:[0,1]
	v_and_or_b32 v64, v161, s53, v155
	v_lshlrev_b32_e32 v161, 5, v64
	v_lshl_add_u64 v[170:171], v[170:171], 0, v[150:151]
	s_waitcnt vmcnt(1)
	v_pk_mul_f32 v[64:65], v[74:75], v[164:165]
	v_pk_mul_f32 v[68:69], v[174:175], v[162:163]
	v_pk_mul_f32 v[72:73], v[78:79], v[164:165]
	v_pk_mul_f32 v[180:181], v[172:173], v[162:163]
	v_pk_mul_f32 v[182:183], v[66:67], v[164:165]
	v_pk_mul_f32 v[184:185], v[178:179], v[162:163]
	v_pk_mul_f32 v[164:165], v[70:71], v[164:165]
	v_pk_mul_f32 v[162:163], v[176:177], v[162:163]
	s_waitcnt vmcnt(0)
	v_pk_fma_f32 v[76:77], v[78:79], v[168:169], v[64:65] neg_lo:[0,0,1] neg_hi:[0,0,1]
	v_pk_fma_f32 v[78:79], v[172:173], v[166:167], v[68:69] neg_lo:[0,0,1] neg_hi:[0,0,1]
	v_pk_fma_f32 v[72:73], v[74:75], v[168:169], v[72:73]
	v_pk_fma_f32 v[74:75], v[174:175], v[166:167], v[180:181]
	v_pk_fma_f32 v[64:65], v[66:67], v[168:169], v[164:165]
	v_pk_fma_f32 v[66:67], v[178:179], v[166:167], v[162:163]
	v_cvt_pk_bf16_f32 v162, v78, v79
	v_cvt_pk_bf16_f32 v163, v76, v77
	v_cvt_pk_bf16_f32 v164, v74, v75
	v_cvt_pk_bf16_f32 v165, v72, v73
	v_pk_fma_f32 v[68:69], v[70:71], v[168:169], v[182:183] neg_lo:[0,0,1] neg_hi:[0,0,1]
	v_pk_fma_f32 v[70:71], v[176:177], v[166:167], v[184:185] neg_lo:[0,0,1] neg_hi:[0,0,1]
	global_store_dwordx4 v[170:171], v[162:165], off nt
	v_pk_mul_f32 v[172:173], v[136:137], v[60:61] op_sel_hi:[0,1]
	v_pk_mul_f32 v[174:175], v[136:137], v[56:57] op_sel_hi:[0,1]
	v_cvt_pk_bf16_f32 v162, v70, v71
	v_cvt_pk_bf16_f32 v163, v68, v69
	v_cvt_pk_bf16_f32 v164, v66, v67
	v_cvt_pk_bf16_f32 v165, v64, v65
	global_store_dwordx4 v[170:171], v[162:165], off offset:256 nt
	global_load_dwordx4 v[162:165], v161, s[14:15] offset:16
	s_nop 0
	global_load_dwordx4 v[166:169], v161, s[14:15]
	v_add_u32_e32 v161, 0x90, v160
	v_lshlrev_b32_e32 v180, 3, v161
	v_pk_mul_f32 v[176:177], v[136:137], v[52:53] op_sel_hi:[0,1]
	v_pk_mul_f32 v[178:179], v[136:137], v[48:49] op_sel_hi:[0,1]
	v_and_or_b32 v48, v180, s54, v155
	v_mad_i64_i32 v[170:171], s[2:3], v186, s51, v[148:149]
	v_lshlrev_b32_e32 v186, 5, v48
	v_lshl_add_u64 v[170:171], v[170:171], 0, v[150:151]
	s_waitcnt vmcnt(1)
	v_pk_mul_f32 v[48:49], v[58:59], v[164:165]
	v_pk_mul_f32 v[52:53], v[174:175], v[162:163]
	v_pk_mul_f32 v[56:57], v[62:63], v[164:165]
	v_pk_mul_f32 v[180:181], v[172:173], v[162:163]
	v_pk_mul_f32 v[182:183], v[50:51], v[164:165]
	v_pk_mul_f32 v[184:185], v[178:179], v[162:163]
	v_pk_mul_f32 v[164:165], v[54:55], v[164:165]
	v_pk_mul_f32 v[162:163], v[176:177], v[162:163]
	s_waitcnt vmcnt(0)
	v_pk_fma_f32 v[60:61], v[62:63], v[168:169], v[48:49] neg_lo:[0,0,1] neg_hi:[0,0,1]
	v_pk_fma_f32 v[62:63], v[172:173], v[166:167], v[52:53] neg_lo:[0,0,1] neg_hi:[0,0,1]
	v_pk_fma_f32 v[56:57], v[58:59], v[168:169], v[56:57]
	v_pk_fma_f32 v[58:59], v[174:175], v[166:167], v[180:181]
	v_pk_fma_f32 v[48:49], v[50:51], v[168:169], v[164:165]
	v_pk_fma_f32 v[50:51], v[178:179], v[166:167], v[162:163]
	v_cvt_pk_bf16_f32 v162, v62, v63
	v_cvt_pk_bf16_f32 v163, v60, v61
	v_cvt_pk_bf16_f32 v164, v58, v59
	v_cvt_pk_bf16_f32 v165, v56, v57
	v_pk_fma_f32 v[52:53], v[54:55], v[168:169], v[182:183] neg_lo:[0,0,1] neg_hi:[0,0,1]
	v_pk_fma_f32 v[54:55], v[176:177], v[166:167], v[184:185] neg_lo:[0,0,1] neg_hi:[0,0,1]
	global_store_dwordx4 v[170:171], v[162:165], off nt
	v_pk_mul_f32 v[172:173], v[136:137], v[44:45] op_sel_hi:[0,1]
	v_pk_mul_f32 v[174:175], v[136:137], v[40:41] op_sel_hi:[0,1]
	v_cvt_pk_bf16_f32 v162, v54, v55
	v_cvt_pk_bf16_f32 v163, v52, v53
	v_cvt_pk_bf16_f32 v164, v50, v51
	v_cvt_pk_bf16_f32 v165, v48, v49
	global_store_dwordx4 v[170:171], v[162:165], off offset:256 nt
	global_load_dwordx4 v[162:165], v186, s[14:15] offset:16
	s_nop 0
	global_load_dwordx4 v[166:169], v186, s[14:15]
	v_add_u32_e32 v186, 0xa0, v160
	v_mad_i64_i32 v[170:171], s[2:3], v161, s51, v[148:149]
	v_lshlrev_b32_e32 v161, 3, v186
	v_pk_mul_f32 v[176:177], v[136:137], v[36:37] op_sel_hi:[0,1]
	v_pk_mul_f32 v[178:179], v[136:137], v[32:33] op_sel_hi:[0,1]
	v_and_or_b32 v32, v161, s55, v155
	v_lshlrev_b32_e32 v161, 5, v32
	v_lshl_add_u64 v[170:171], v[170:171], 0, v[150:151]
	s_waitcnt vmcnt(1)
	v_pk_mul_f32 v[32:33], v[42:43], v[164:165]
	v_pk_mul_f32 v[36:37], v[174:175], v[162:163]
	v_pk_mul_f32 v[40:41], v[46:47], v[164:165]
	v_pk_mul_f32 v[180:181], v[172:173], v[162:163]
	v_pk_mul_f32 v[182:183], v[34:35], v[164:165]
	v_pk_mul_f32 v[184:185], v[178:179], v[162:163]
	v_pk_mul_f32 v[164:165], v[38:39], v[164:165]
	v_pk_mul_f32 v[162:163], v[176:177], v[162:163]
	s_waitcnt vmcnt(0)
	v_pk_fma_f32 v[44:45], v[46:47], v[168:169], v[32:33] neg_lo:[0,0,1] neg_hi:[0,0,1]
	v_pk_fma_f32 v[46:47], v[172:173], v[166:167], v[36:37] neg_lo:[0,0,1] neg_hi:[0,0,1]
	v_pk_fma_f32 v[40:41], v[42:43], v[168:169], v[40:41]
	v_pk_fma_f32 v[42:43], v[174:175], v[166:167], v[180:181]
	v_pk_fma_f32 v[32:33], v[34:35], v[168:169], v[164:165]
	v_pk_fma_f32 v[34:35], v[178:179], v[166:167], v[162:163]
	v_cvt_pk_bf16_f32 v162, v46, v47
	v_cvt_pk_bf16_f32 v163, v44, v45
	v_cvt_pk_bf16_f32 v164, v42, v43
	v_cvt_pk_bf16_f32 v165, v40, v41
	v_pk_fma_f32 v[36:37], v[38:39], v[168:169], v[182:183] neg_lo:[0,0,1] neg_hi:[0,0,1]
	v_pk_fma_f32 v[38:39], v[176:177], v[166:167], v[184:185] neg_lo:[0,0,1] neg_hi:[0,0,1]
	global_store_dwordx4 v[170:171], v[162:165], off nt
	v_add_u32_e32 v184, 0xb0, v160
	v_lshlrev_b32_e32 v178, 3, v184
	v_cvt_pk_bf16_f32 v162, v38, v39
	v_cvt_pk_bf16_f32 v163, v36, v37
	v_cvt_pk_bf16_f32 v164, v34, v35
	v_cvt_pk_bf16_f32 v165, v32, v33
	global_store_dwordx4 v[170:171], v[162:165], off offset:256 nt
	global_load_dwordx4 v[162:165], v161, s[14:15] offset:16
	s_nop 0
	global_load_dwordx4 v[166:169], v161, s[14:15]
	v_mad_i64_i32 v[160:161], s[2:3], v186, s51, v[148:149]
	v_lshl_add_u64 v[170:171], v[160:161], 0, v[150:151]
	v_pk_mul_f32 v[160:161], v[136:137], v[28:29] op_sel_hi:[0,1]
	v_pk_mul_f32 v[172:173], v[136:137], v[24:25] op_sel_hi:[0,1]
	v_pk_mul_f32 v[174:175], v[136:137], v[20:21] op_sel_hi:[0,1]
	v_pk_mul_f32 v[176:177], v[136:137], v[16:17] op_sel_hi:[0,1]
	v_and_or_b32 v16, v178, s56, v155
	v_lshlrev_b32_e32 v185, 5, v16
	v_mad_i64_i32 v[148:149], s[2:3], v184, s51, v[148:149]
	s_waitcnt vmcnt(1)
	v_pk_mul_f32 v[16:17], v[26:27], v[164:165]
	v_pk_mul_f32 v[20:21], v[172:173], v[162:163]
	v_pk_mul_f32 v[24:25], v[30:31], v[164:165]
	v_pk_mul_f32 v[178:179], v[160:161], v[162:163]
	v_pk_mul_f32 v[180:181], v[18:19], v[164:165]
	v_pk_mul_f32 v[182:183], v[176:177], v[162:163]
	v_pk_mul_f32 v[164:165], v[22:23], v[164:165]
	v_pk_mul_f32 v[162:163], v[174:175], v[162:163]
	s_waitcnt vmcnt(0)
	v_pk_fma_f32 v[28:29], v[30:31], v[168:169], v[16:17] neg_lo:[0,0,1] neg_hi:[0,0,1]
	v_pk_fma_f32 v[30:31], v[160:161], v[166:167], v[20:21] neg_lo:[0,0,1] neg_hi:[0,0,1]
	v_pk_fma_f32 v[24:25], v[26:27], v[168:169], v[24:25]
	v_pk_fma_f32 v[26:27], v[172:173], v[166:167], v[178:179]
	v_pk_fma_f32 v[16:17], v[18:19], v[168:169], v[164:165]
	v_pk_fma_f32 v[18:19], v[176:177], v[166:167], v[162:163]
	v_cvt_pk_bf16_f32 v160, v30, v31
	v_cvt_pk_bf16_f32 v161, v28, v29
	v_cvt_pk_bf16_f32 v162, v26, v27
	v_cvt_pk_bf16_f32 v163, v24, v25
	v_pk_fma_f32 v[20:21], v[22:23], v[168:169], v[180:181] neg_lo:[0,0,1] neg_hi:[0,0,1]
	v_pk_fma_f32 v[22:23], v[174:175], v[166:167], v[182:183] neg_lo:[0,0,1] neg_hi:[0,0,1]
	global_store_dwordx4 v[170:171], v[160:163], off nt
	v_lshl_add_u64 v[168:169], v[148:149], 0, v[150:151]
	v_pk_mul_f32 v[148:149], v[136:137], v[12:13] op_sel_hi:[0,1]
	v_cvt_pk_bf16_f32 v160, v22, v23
	v_cvt_pk_bf16_f32 v161, v20, v21
	v_cvt_pk_bf16_f32 v162, v18, v19
	v_cvt_pk_bf16_f32 v163, v16, v17
	global_store_dwordx4 v[170:171], v[160:163], off offset:256 nt
	global_load_dwordx4 v[160:163], v185, s[14:15] offset:16
	s_nop 0
	global_load_dwordx4 v[164:167], v185, s[14:15]
	v_pk_mul_f32 v[150:151], v[136:137], v[8:9] op_sel_hi:[0,1]
	v_pk_mul_f32 v[170:171], v[136:137], v[4:5] op_sel_hi:[0,1]
	v_pk_mul_f32 v[172:173], v[136:137], v[0:1] op_sel_hi:[0,1]
	s_waitcnt vmcnt(1)
	v_pk_mul_f32 v[0:1], v[10:11], v[162:163]
	v_pk_mul_f32 v[4:5], v[150:151], v[160:161]
	v_pk_mul_f32 v[8:9], v[14:15], v[162:163]
	v_pk_mul_f32 v[174:175], v[148:149], v[160:161]
	v_pk_mul_f32 v[176:177], v[2:3], v[162:163]
	v_pk_mul_f32 v[178:179], v[172:173], v[160:161]
	v_pk_mul_f32 v[162:163], v[6:7], v[162:163]
	v_pk_mul_f32 v[160:161], v[170:171], v[160:161]
	s_waitcnt vmcnt(0)
	v_pk_fma_f32 v[12:13], v[14:15], v[166:167], v[0:1] neg_lo:[0,0,1] neg_hi:[0,0,1]
	v_pk_fma_f32 v[14:15], v[148:149], v[164:165], v[4:5] neg_lo:[0,0,1] neg_hi:[0,0,1]
	v_pk_fma_f32 v[8:9], v[10:11], v[166:167], v[8:9]
	v_pk_fma_f32 v[10:11], v[150:151], v[164:165], v[174:175]
	v_pk_fma_f32 v[4:5], v[6:7], v[166:167], v[176:177] neg_lo:[0,0,1] neg_hi:[0,0,1]
	v_pk_fma_f32 v[6:7], v[170:171], v[164:165], v[178:179] neg_lo:[0,0,1] neg_hi:[0,0,1]
	v_pk_fma_f32 v[0:1], v[2:3], v[166:167], v[162:163]
	v_pk_fma_f32 v[2:3], v[172:173], v[164:165], v[160:161]
	v_cvt_pk_bf16_f32 v148, v14, v15
	v_cvt_pk_bf16_f32 v149, v12, v13
	v_cvt_pk_bf16_f32 v150, v10, v11
	v_cvt_pk_bf16_f32 v151, v8, v9
	global_store_dwordx4 v[168:169], v[148:151], off nt
	s_nop 1
	v_cvt_pk_bf16_f32 v148, v6, v7
	v_cvt_pk_bf16_f32 v149, v4, v5
	v_cvt_pk_bf16_f32 v150, v2, v3
	v_cvt_pk_bf16_f32 v151, v0, v1
	global_store_dwordx4 v[168:169], v[148:151], off offset:256 nt
	s_cbranch_scc1 .LBB0_291
	v_pk_add_f32 v[126:127], v[126:127], 0 op_sel_hi:[1,0]
	s_add_i32 s4, s1, 0xfffffe00
	v_pk_add_f32 v[110:111], v[126:127], v[110:111]
	s_nop 0
	v_pk_add_f32 v[94:95], v[110:111], v[94:95]
	s_nop 0
	v_pk_add_f32 v[78:79], v[94:95], v[78:79]
	s_nop 0
	v_pk_add_f32 v[62:63], v[78:79], v[62:63]
	s_nop 0
	v_pk_add_f32 v[46:47], v[62:63], v[46:47]
	s_nop 0
	v_pk_add_f32 v[30:31], v[46:47], v[30:31]
	s_nop 0
	v_pk_add_f32 v[14:15], v[30:31], v[14:15]
	v_mov_b32_e32 v31, v137
	s_nop 0
	v_add_f32_dpp v14, v14, v14 row_ror:8 row_mask:0xf bank_mask:0xf bound_ctrl:1
	s_nop 1
	v_add_f32_dpp v14, v14, v14 row_ror:4 row_mask:0xf bank_mask:0xf bound_ctrl:1
	s_nop 1
	v_add_f32_dpp v30, v14, v14 row_ror:2 row_mask:0xf bank_mask:0xf bound_ctrl:1
	v_lshlrev_b32_e32 v14, 2, v138
	s_nop 0
	v_mov_b32_dpp v31, v30 row_ror:1 row_mask:0xf bank_mask:0xf
	s_and_saveexec_b64 s[2:3], s[6:7]
	s_cbranch_execz .LBB0_260
	s_ashr_i32 s1, s0, 31
	s_lshl_b64 s[10:11], s[0:1], 11
	s_add_u32 s1, s16, s10
	s_addc_u32 s27, s17, s11
	s_lshl_b64 s[10:11], s[4:5], 2
	s_add_u32 s1, s1, s10
	s_addc_u32 s11, s27, s11
	s_lshl_b32 s10, s42, 2
	s_add_u32 s10, s1, s10
	v_add_f32_e32 v30, v30, v31
	s_addc_u32 s11, s11, 0
	global_atomic_add_f32 v14, v30, s[10:11]

.LBB0_1052:
	v_lshl_add_u32 v144, s0, 8, v148
	v_ashrrev_i32_e32 v145, 31, v144
	v_lshl_add_u64 v[146:147], v[144:145], 2, s[54:55]
	global_load_dword v145, v[146:147], off
	global_load_dword v247, v[146:147], off offset:64
	global_load_dword v248, v[146:147], off offset:128
	global_load_dword v249, v[146:147], off offset:192
	global_load_dword v250, v[146:147], off offset:512
	global_load_dword v251, v[146:147], off offset:576
	global_load_dword v252, v[146:147], off offset:640
	global_load_dword v253, v[146:147], off offset:704
	v_lshl_or_b32 v156, s1, 7, v150
	v_readlane_b32 s0, v246, 26
	v_mov_b32_e32 v161, v114
	v_mov_b32_e32 v114, v123
	v_readlane_b32 s1, v246, 27
	v_mov_b32_e32 v158, v124
	v_mov_b32_e32 v159, v116
	v_mov_b32_e32 v116, v125
	v_mov_b32_e32 v124, v126
	v_mov_b32_e32 v125, v118
	v_mov_b32_e32 v118, v127
	v_mov_b32_e32 v126, v120
	v_mov_b32_e32 v127, v112
	v_mov_b32_e32 v112, v121
	v_mov_b32_e32 v160, v122
	v_mov_b64_e32 v[120:121], s[0:1]
	v_ashrrev_i32_e32 v157, 31, v156
	v_or_b32_e32 v164, 16, v144
	v_mad_i64_i32 v[162:163], s[0:1], v144, s44, v[120:121]
	v_lshlrev_b64 v[122:123], 1, v[156:157]
	v_ashrrev_i32_e32 v165, 31, v164
	v_lshl_add_u64 v[156:157], v[162:163], 0, v[122:123]
	v_lshl_add_u64 v[162:163], v[164:165], 2, s[54:55]
	s_waitcnt vmcnt(7)
	v_fmamk_f32 v145, v145, 0x3a800000, v154
	v_mul_f32_e32 v155, 0x4b800000, v145
	v_cmp_gt_f32_e32 vcc, s43, v145
	s_nop 1
	v_cndmask_b32_e32 v145, v145, v155, vcc
	v_rsq_f32_e32 v145, v145
	s_nop 0
	v_mul_f32_e32 v155, 0x45800000, v145
	v_cndmask_b32_e32 v166, v145, v155, vcc
	v_pk_mul_f32 v[114:115], v[114:115], v[166:167] op_sel_hi:[1,0]
	v_pk_mul_f32 v[158:159], v[158:159], v[166:167] op_sel_hi:[1,0]
	v_pk_mul_f32 v[116:117], v[116:117], v[166:167] op_sel_hi:[1,0]
	v_pk_mul_f32 v[124:125], v[124:125], v[166:167] op_sel_hi:[1,0]
	v_pk_mul_f32 v[118:119], v[118:119], v[166:167] op_sel_hi:[1,0]
	v_pk_mul_f32 v[126:127], v[126:127], v[166:167] op_sel_hi:[1,0]
	v_pk_mul_f32 v[112:113], v[112:113], v[166:167] op_sel_hi:[1,0]
	v_pk_mul_f32 v[160:161], v[160:161], v[166:167] op_sel_hi:[1,0]
	v_mul_f32_e32 v170, 0xbfb8aa3b, v115
	v_mul_f32_e32 v145, 0xbfb8aa3b, v159
	v_mul_f32_e32 v155, 0xbfb8aa3b, v117
	v_mul_f32_e32 v165, 0xbfb8aa3b, v125
	v_mul_f32_e32 v166, 0xbfb8aa3b, v119
	v_mul_f32_e32 v167, 0xbfb8aa3b, v127
	v_mul_f32_e32 v168, 0xbfb8aa3b, v113
	v_mul_f32_e32 v169, 0xbfb8aa3b, v161
	v_exp_f32_e32 v170, v170
	v_exp_f32_e32 v145, v145
	v_exp_f32_e32 v155, v155
	v_exp_f32_e32 v165, v165
	v_exp_f32_e32 v166, v166
	v_exp_f32_e32 v167, v167
	v_exp_f32_e32 v168, v168
	v_exp_f32_e32 v169, v169
	v_add_f32_e32 v170, 1.0, v170
	v_add_f32_e32 v145, 1.0, v145
	v_add_f32_e32 v155, 1.0, v155
	v_add_f32_e32 v165, 1.0, v165
	v_add_f32_e32 v166, 1.0, v166
	v_add_f32_e32 v167, 1.0, v167
	v_add_f32_e32 v168, 1.0, v168
	v_add_f32_e32 v169, 1.0, v169
	v_rcp_f32_e32 v170, v170
	v_rcp_f32_e32 v145, v145
	v_rcp_f32_e32 v155, v155
	v_rcp_f32_e32 v165, v165
	v_rcp_f32_e32 v166, v166
	v_rcp_f32_e32 v167, v167
	v_rcp_f32_e32 v168, v168
	v_rcp_f32_e32 v169, v169
	v_mul_f32_e32 v115, v115, v170
	v_mul_f32_e32 v145, v159, v145
	v_mul_f32_e32 v117, v117, v155
	v_mul_f32_e32 v125, v125, v165
	v_mul_f32_e32 v119, v119, v166
	v_mul_f32_e32 v127, v127, v167
	v_mul_f32_e32 v113, v113, v168
	v_mul_f32_e32 v155, v161, v169
	v_mul_f32_e32 v115, v114, v115
	v_mul_f32_e32 v145, v158, v145
	v_mul_f32_e32 v116, v116, v117
	v_mul_f32_e32 v117, v124, v125
	v_mul_f32_e32 v118, v118, v119
	v_mul_f32_e32 v119, v126, v127
	v_mul_f32_e32 v124, v112, v113
	v_mul_f32_e32 v125, v160, v155
	v_cvt_pk_bf16_f32 v112, v145, v116
	v_cvt_pk_bf16_f32 v113, v117, v118
	v_cvt_pk_bf16_f32 v114, v119, v124
	v_cvt_pk_bf16_f32 v115, v125, v115
	global_store_dwordx4 v[156:157], v[112:115], off nt
	s_nop 0
	s_nop 0
	v_mov_b32_e32 v113, v100
	v_mov_b32_e32 v100, v109
	v_mov_b32_e32 v109, v102
	v_mov_b32_e32 v102, v111
	v_mov_b32_e32 v111, v96
	v_mov_b32_e32 v96, v105
	v_mov_b32_e32 v105, v98
	v_mov_b32_e32 v98, v107
	v_mov_b32_e32 v112, v108
	v_mov_b32_e32 v108, v110
	v_mov_b32_e32 v110, v104
	v_mov_b32_e32 v104, v106
	v_or_b32_e32 v106, 32, v144
	v_mad_i64_i32 v[114:115], s[0:1], v164, s44, v[120:121]
	v_lshl_add_u64 v[114:115], v[114:115], 0, v[122:123]
	s_waitcnt vmcnt(7)
	v_mov_b32_e32 v116, v247
	v_fmamk_f32 v107, v116, 0x3a800000, v154
	v_mul_f32_e32 v116, 0x4b800000, v107
	v_cmp_gt_f32_e32 vcc, s43, v107
	s_nop 1
	v_cndmask_b32_e32 v107, v107, v116, vcc
	v_rsq_f32_e32 v118, v107
	v_ashrrev_i32_e32 v107, 31, v106
	v_lshl_add_u64 v[116:117], v[106:107], 2, s[54:55]
	v_mul_f32_e32 v107, 0x45800000, v118
	v_cndmask_b32_e32 v118, v118, v107, vcc
	v_pk_mul_f32 v[98:99], v[98:99], v[118:119] op_sel_hi:[1,0]
	v_pk_mul_f32 v[112:113], v[112:113], v[118:119] op_sel_hi:[1,0]
	v_pk_mul_f32 v[100:101], v[100:101], v[118:119] op_sel_hi:[1,0]
	v_pk_mul_f32 v[108:109], v[108:109], v[118:119] op_sel_hi:[1,0]
	v_pk_mul_f32 v[102:103], v[102:103], v[118:119] op_sel_hi:[1,0]
	v_pk_mul_f32 v[110:111], v[110:111], v[118:119] op_sel_hi:[1,0]
	v_pk_mul_f32 v[96:97], v[96:97], v[118:119] op_sel_hi:[1,0]
	v_pk_mul_f32 v[104:105], v[104:105], v[118:119] op_sel_hi:[1,0]
	v_mul_f32_e32 v145, 0xbfb8aa3b, v99
	v_mul_f32_e32 v107, 0xbfb8aa3b, v113
	v_mul_f32_e32 v118, 0xbfb8aa3b, v101
	v_mul_f32_e32 v119, 0xbfb8aa3b, v109
	v_mul_f32_e32 v124, 0xbfb8aa3b, v103
	v_mul_f32_e32 v125, 0xbfb8aa3b, v111
	v_mul_f32_e32 v126, 0xbfb8aa3b, v97
	v_mul_f32_e32 v127, 0xbfb8aa3b, v105
	v_exp_f32_e32 v145, v145
	v_exp_f32_e32 v107, v107
	v_exp_f32_e32 v118, v118
	v_exp_f32_e32 v119, v119
	v_exp_f32_e32 v124, v124
	v_exp_f32_e32 v125, v125
	v_exp_f32_e32 v126, v126
	v_exp_f32_e32 v127, v127
	v_add_f32_e32 v145, 1.0, v145
	v_add_f32_e32 v107, 1.0, v107
	v_add_f32_e32 v118, 1.0, v118
	v_add_f32_e32 v119, 1.0, v119
	v_add_f32_e32 v124, 1.0, v124
	v_add_f32_e32 v125, 1.0, v125
	v_add_f32_e32 v126, 1.0, v126
	v_add_f32_e32 v127, 1.0, v127
	v_rcp_f32_e32 v145, v145
	v_rcp_f32_e32 v107, v107
	v_rcp_f32_e32 v118, v118
	v_rcp_f32_e32 v119, v119
	v_rcp_f32_e32 v124, v124
	v_rcp_f32_e32 v125, v125
	v_rcp_f32_e32 v126, v126
	v_rcp_f32_e32 v127, v127
	v_mul_f32_e32 v99, v99, v145
	v_mul_f32_e32 v107, v113, v107
	v_mul_f32_e32 v101, v101, v118
	v_mul_f32_e32 v109, v109, v119
	v_mul_f32_e32 v103, v103, v124
	v_mul_f32_e32 v111, v111, v125
	v_mul_f32_e32 v97, v97, v126
	v_mul_f32_e32 v105, v105, v127
	v_mul_f32_e32 v99, v98, v99
	v_mul_f32_e32 v107, v112, v107
	v_mul_f32_e32 v100, v100, v101
	v_mul_f32_e32 v101, v108, v109
	v_mul_f32_e32 v102, v102, v103
	v_mul_f32_e32 v103, v110, v111
	v_mul_f32_e32 v108, v96, v97
	v_mul_f32_e32 v104, v104, v105
	v_cvt_pk_bf16_f32 v96, v107, v100
	v_cvt_pk_bf16_f32 v97, v101, v102
	v_cvt_pk_bf16_f32 v98, v103, v108
	v_cvt_pk_bf16_f32 v99, v104, v99
	global_store_dwordx4 v[114:115], v[96:99], off nt
	s_nop 0
	s_nop 0
	v_mov_b32_e32 v97, v84
	v_mov_b32_e32 v84, v93
	v_mov_b32_e32 v93, v86
	v_mov_b32_e32 v86, v95
	v_mov_b32_e32 v95, v80
	v_mov_b32_e32 v80, v89
	v_mov_b32_e32 v89, v82
	v_mov_b32_e32 v82, v91
	v_mov_b32_e32 v96, v92
	v_mov_b32_e32 v92, v94
	v_mov_b32_e32 v94, v88
	v_mov_b32_e32 v88, v90
	v_or_b32_e32 v90, 48, v144
	v_mad_i64_i32 v[98:99], s[0:1], v106, s44, v[120:121]
	v_lshl_add_u64 v[98:99], v[98:99], 0, v[122:123]
	s_waitcnt vmcnt(7)
	v_mov_b32_e32 v100, v248
	v_fmamk_f32 v91, v100, 0x3a800000, v154
	v_mul_f32_e32 v100, 0x4b800000, v91
	v_cmp_gt_f32_e32 vcc, s43, v91
	s_nop 1
	v_cndmask_b32_e32 v91, v91, v100, vcc
	v_rsq_f32_e32 v102, v91
	v_ashrrev_i32_e32 v91, 31, v90
	v_lshl_add_u64 v[100:101], v[90:91], 2, s[54:55]
	v_mul_f32_e32 v91, 0x45800000, v102
	v_cndmask_b32_e32 v102, v102, v91, vcc
	v_pk_mul_f32 v[82:83], v[82:83], v[102:103] op_sel_hi:[1,0]
	v_pk_mul_f32 v[96:97], v[96:97], v[102:103] op_sel_hi:[1,0]
	v_pk_mul_f32 v[84:85], v[84:85], v[102:103] op_sel_hi:[1,0]
	v_pk_mul_f32 v[92:93], v[92:93], v[102:103] op_sel_hi:[1,0]
	v_pk_mul_f32 v[86:87], v[86:87], v[102:103] op_sel_hi:[1,0]
	v_pk_mul_f32 v[94:95], v[94:95], v[102:103] op_sel_hi:[1,0]
	v_pk_mul_f32 v[80:81], v[80:81], v[102:103] op_sel_hi:[1,0]
	v_pk_mul_f32 v[88:89], v[88:89], v[102:103] op_sel_hi:[1,0]
	v_mul_f32_e32 v108, 0xbfb8aa3b, v83
	v_mul_f32_e32 v91, 0xbfb8aa3b, v97
	v_mul_f32_e32 v102, 0xbfb8aa3b, v85
	v_mul_f32_e32 v103, 0xbfb8aa3b, v93
	v_mul_f32_e32 v104, 0xbfb8aa3b, v87
	v_mul_f32_e32 v105, 0xbfb8aa3b, v95
	v_mul_f32_e32 v106, 0xbfb8aa3b, v81
	v_mul_f32_e32 v107, 0xbfb8aa3b, v89
	v_exp_f32_e32 v108, v108
	v_exp_f32_e32 v91, v91
	v_exp_f32_e32 v102, v102
	v_exp_f32_e32 v103, v103
	v_exp_f32_e32 v104, v104
	v_exp_f32_e32 v105, v105
	v_exp_f32_e32 v106, v106
	v_exp_f32_e32 v107, v107
	v_add_f32_e32 v108, 1.0, v108
	v_add_f32_e32 v91, 1.0, v91
	v_add_f32_e32 v102, 1.0, v102
	v_add_f32_e32 v103, 1.0, v103
	v_add_f32_e32 v104, 1.0, v104
	v_add_f32_e32 v105, 1.0, v105
	v_add_f32_e32 v106, 1.0, v106
	v_add_f32_e32 v107, 1.0, v107
	v_rcp_f32_e32 v108, v108
	v_rcp_f32_e32 v91, v91
	v_rcp_f32_e32 v102, v102
	v_rcp_f32_e32 v103, v103
	v_rcp_f32_e32 v104, v104
	v_rcp_f32_e32 v105, v105
	v_rcp_f32_e32 v106, v106
	v_rcp_f32_e32 v107, v107
	v_mul_f32_e32 v83, v83, v108
	v_mul_f32_e32 v91, v97, v91
	v_mul_f32_e32 v85, v85, v102
	v_mul_f32_e32 v93, v93, v103
	v_mul_f32_e32 v87, v87, v104
	v_mul_f32_e32 v95, v95, v105
	v_mul_f32_e32 v81, v81, v106
	v_mul_f32_e32 v89, v89, v107
	v_mul_f32_e32 v83, v82, v83
	v_mul_f32_e32 v91, v96, v91
	v_mul_f32_e32 v84, v84, v85
	v_mul_f32_e32 v85, v92, v93
	v_mul_f32_e32 v86, v86, v87
	v_mul_f32_e32 v87, v94, v95
	v_mul_f32_e32 v92, v80, v81
	v_mul_f32_e32 v88, v88, v89
	v_cvt_pk_bf16_f32 v80, v91, v84
	v_cvt_pk_bf16_f32 v81, v85, v86
	v_cvt_pk_bf16_f32 v82, v87, v92
	v_cvt_pk_bf16_f32 v83, v88, v83
	global_store_dwordx4 v[98:99], v[80:83], off nt
	s_nop 0
	s_nop 0
	v_mov_b32_e32 v80, v76
	v_mov_b32_e32 v76, v78
	v_mov_b32_e32 v78, v68
	v_mov_b32_e32 v68, v70
	v_mov_b32_e32 v81, v72
	v_mov_b32_e32 v72, v77
	v_mov_b32_e32 v77, v74
	v_mov_b32_e32 v74, v79
	v_mov_b32_e32 v79, v64
	v_mov_b32_e32 v64, v69
	v_mov_b32_e32 v69, v66
	v_mov_b32_e32 v66, v71
	s_waitcnt vmcnt(7)
	v_mov_b32_e32 v82, v249
	v_fmamk_f32 v70, v82, 0x3a800000, v154
	v_mul_f32_e32 v71, 0x4b800000, v70
	v_cmp_gt_f32_e32 vcc, s43, v70
	s_nop 1
	v_cndmask_b32_e32 v70, v70, v71, vcc
	v_rsq_f32_e32 v82, v70
	v_mad_i64_i32 v[70:71], s[0:1], v90, s44, v[120:121]
	v_lshl_add_u64 v[70:71], v[70:71], 0, v[122:123]
	v_mul_f32_e32 v83, 0x45800000, v82
	v_cndmask_b32_e32 v82, v82, v83, vcc
	v_pk_mul_f32 v[66:67], v[66:67], v[82:83] op_sel_hi:[1,0]
	v_pk_mul_f32 v[80:81], v[80:81], v[82:83] op_sel_hi:[1,0]
	v_pk_mul_f32 v[72:73], v[72:73], v[82:83] op_sel_hi:[1,0]
	v_pk_mul_f32 v[76:77], v[76:77], v[82:83] op_sel_hi:[1,0]
	v_pk_mul_f32 v[74:75], v[74:75], v[82:83] op_sel_hi:[1,0]
	v_pk_mul_f32 v[78:79], v[78:79], v[82:83] op_sel_hi:[1,0]
	v_pk_mul_f32 v[64:65], v[64:65], v[82:83] op_sel_hi:[1,0]
	v_pk_mul_f32 v[68:69], v[68:69], v[82:83] op_sel_hi:[1,0]
	v_mul_f32_e32 v89, 0xbfb8aa3b, v67
	v_mul_f32_e32 v82, 0xbfb8aa3b, v81
	v_mul_f32_e32 v83, 0xbfb8aa3b, v73
	v_mul_f32_e32 v84, 0xbfb8aa3b, v77
	v_mul_f32_e32 v85, 0xbfb8aa3b, v75
	v_mul_f32_e32 v86, 0xbfb8aa3b, v79
	v_mul_f32_e32 v87, 0xbfb8aa3b, v65
	v_mul_f32_e32 v88, 0xbfb8aa3b, v69
	v_exp_f32_e32 v89, v89
	v_exp_f32_e32 v82, v82
	v_exp_f32_e32 v83, v83
	v_exp_f32_e32 v84, v84
	v_exp_f32_e32 v85, v85
	v_exp_f32_e32 v86, v86
	v_exp_f32_e32 v87, v87
	v_exp_f32_e32 v88, v88
	v_add_f32_e32 v89, 1.0, v89
	v_add_f32_e32 v82, 1.0, v82
	v_add_f32_e32 v83, 1.0, v83
	v_add_f32_e32 v84, 1.0, v84
	v_add_f32_e32 v85, 1.0, v85
	v_add_f32_e32 v86, 1.0, v86
	v_add_f32_e32 v87, 1.0, v87
	v_add_f32_e32 v88, 1.0, v88
	v_rcp_f32_e32 v89, v89
	v_rcp_f32_e32 v82, v82
	v_rcp_f32_e32 v83, v83
	v_rcp_f32_e32 v84, v84
	v_rcp_f32_e32 v85, v85
	v_rcp_f32_e32 v86, v86
	v_rcp_f32_e32 v87, v87
	v_rcp_f32_e32 v88, v88
	v_mul_f32_e32 v67, v67, v89
	v_mul_f32_e32 v81, v81, v82
	v_mul_f32_e32 v73, v73, v83
	v_mul_f32_e32 v77, v77, v84
	v_mul_f32_e32 v75, v75, v85
	v_mul_f32_e32 v79, v79, v86
	v_mul_f32_e32 v65, v65, v87
	v_mul_f32_e32 v69, v69, v88
	v_mul_f32_e32 v67, v66, v67
	v_mul_f32_e32 v80, v80, v81
	v_mul_f32_e32 v72, v72, v73
	v_mul_f32_e32 v73, v76, v77
	v_mul_f32_e32 v74, v74, v75
	v_mul_f32_e32 v75, v78, v79
	v_mul_f32_e32 v76, v64, v65
	v_mul_f32_e32 v68, v68, v69
	v_cvt_pk_bf16_f32 v64, v80, v72
	v_cvt_pk_bf16_f32 v65, v73, v74
	v_cvt_pk_bf16_f32 v66, v75, v76
	v_cvt_pk_bf16_f32 v67, v68, v67
	global_store_dwordx4 v[70:71], v[64:67], off nt
	s_nop 0
	s_nop 0
	v_mov_b32_e32 v65, v56
	v_mov_b32_e32 v56, v61
	v_mov_b32_e32 v61, v58
	v_mov_b32_e32 v58, v63
	v_mov_b32_e32 v63, v48
	v_mov_b32_e32 v48, v53
	v_mov_b32_e32 v53, v50
	v_mov_b32_e32 v50, v55
	v_mov_b32_e32 v64, v60
	v_mov_b32_e32 v60, v62
	v_mov_b32_e32 v62, v52
	v_mov_b32_e32 v52, v54
	v_add_u32_e32 v54, 0x80, v144
	s_waitcnt vmcnt(7)
	v_mov_b32_e32 v66, v250
	v_fmamk_f32 v55, v66, 0x3a800000, v154
	v_mul_f32_e32 v66, 0x4b800000, v55
	v_cmp_gt_f32_e32 vcc, s43, v55
	s_nop 1
	v_cndmask_b32_e32 v55, v55, v66, vcc
	v_rsq_f32_e32 v66, v55
	v_mad_i64_i32 v[54:55], s[0:1], v54, s44, v[120:121]
	v_lshl_add_u64 v[54:55], v[54:55], 0, v[122:123]
	v_mul_f32_e32 v67, 0x45800000, v66
	v_cndmask_b32_e32 v66, v66, v67, vcc
	v_pk_mul_f32 v[50:51], v[50:51], v[66:67] op_sel_hi:[1,0]
	v_pk_mul_f32 v[64:65], v[64:65], v[66:67] op_sel_hi:[1,0]
	v_pk_mul_f32 v[56:57], v[56:57], v[66:67] op_sel_hi:[1,0]
	v_pk_mul_f32 v[60:61], v[60:61], v[66:67] op_sel_hi:[1,0]
	v_pk_mul_f32 v[58:59], v[58:59], v[66:67] op_sel_hi:[1,0]
	v_pk_mul_f32 v[62:63], v[62:63], v[66:67] op_sel_hi:[1,0]
	v_pk_mul_f32 v[48:49], v[48:49], v[66:67] op_sel_hi:[1,0]
	v_pk_mul_f32 v[52:53], v[52:53], v[66:67] op_sel_hi:[1,0]
	v_mul_f32_e32 v73, 0xbfb8aa3b, v51
	v_mul_f32_e32 v66, 0xbfb8aa3b, v65
	v_mul_f32_e32 v67, 0xbfb8aa3b, v57
	v_mul_f32_e32 v68, 0xbfb8aa3b, v61
	v_mul_f32_e32 v69, 0xbfb8aa3b, v59
	v_mul_f32_e32 v70, 0xbfb8aa3b, v63
	v_mul_f32_e32 v71, 0xbfb8aa3b, v49
	v_mul_f32_e32 v72, 0xbfb8aa3b, v53
	v_exp_f32_e32 v73, v73
	v_exp_f32_e32 v66, v66
	v_exp_f32_e32 v67, v67
	v_exp_f32_e32 v68, v68
	v_exp_f32_e32 v69, v69
	v_exp_f32_e32 v70, v70
	v_exp_f32_e32 v71, v71
	v_exp_f32_e32 v72, v72
	v_add_f32_e32 v73, 1.0, v73
	v_add_f32_e32 v66, 1.0, v66
	v_add_f32_e32 v67, 1.0, v67
	v_add_f32_e32 v68, 1.0, v68
	v_add_f32_e32 v69, 1.0, v69
	v_add_f32_e32 v70, 1.0, v70
	v_add_f32_e32 v71, 1.0, v71
	v_add_f32_e32 v72, 1.0, v72
	v_rcp_f32_e32 v73, v73
	v_rcp_f32_e32 v66, v66
	v_rcp_f32_e32 v67, v67
	v_rcp_f32_e32 v68, v68
	v_rcp_f32_e32 v69, v69
	v_rcp_f32_e32 v70, v70
	v_rcp_f32_e32 v71, v71
	v_rcp_f32_e32 v72, v72
	v_mul_f32_e32 v51, v51, v73
	v_mul_f32_e32 v65, v65, v66
	v_mul_f32_e32 v57, v57, v67
	v_mul_f32_e32 v61, v61, v68
	v_mul_f32_e32 v59, v59, v69
	v_mul_f32_e32 v63, v63, v70
	v_mul_f32_e32 v49, v49, v71
	v_mul_f32_e32 v53, v53, v72
	v_mul_f32_e32 v51, v50, v51
	v_mul_f32_e32 v64, v64, v65
	v_mul_f32_e32 v56, v56, v57
	v_mul_f32_e32 v57, v60, v61
	v_mul_f32_e32 v58, v58, v59
	v_mul_f32_e32 v59, v62, v63
	v_mul_f32_e32 v60, v48, v49
	v_mul_f32_e32 v52, v52, v53
	v_cvt_pk_bf16_f32 v48, v64, v56
	v_cvt_pk_bf16_f32 v49, v57, v58
	v_cvt_pk_bf16_f32 v50, v59, v60
	v_cvt_pk_bf16_f32 v51, v52, v51
	global_store_dwordx4 v[54:55], v[48:51], off nt
	s_nop 0
	s_nop 0
	v_mov_b32_e32 v49, v40
	v_mov_b32_e32 v40, v45
	v_mov_b32_e32 v45, v42
	v_mov_b32_e32 v42, v47
	v_mov_b32_e32 v47, v32
	v_mov_b32_e32 v32, v37
	v_mov_b32_e32 v37, v34
	v_mov_b32_e32 v34, v39
	v_mov_b32_e32 v48, v44
	v_mov_b32_e32 v44, v46
	v_mov_b32_e32 v46, v36
	v_mov_b32_e32 v36, v38
	v_add_u32_e32 v38, 0x90, v144
	s_waitcnt vmcnt(7)
	v_mov_b32_e32 v50, v251
	v_fmamk_f32 v39, v50, 0x3a800000, v154
	v_mul_f32_e32 v50, 0x4b800000, v39
	v_cmp_gt_f32_e32 vcc, s43, v39
	s_nop 1
	v_cndmask_b32_e32 v39, v39, v50, vcc
	v_rsq_f32_e32 v50, v39
	v_mad_i64_i32 v[38:39], s[0:1], v38, s44, v[120:121]
	v_lshl_add_u64 v[38:39], v[38:39], 0, v[122:123]
	v_mul_f32_e32 v51, 0x45800000, v50
	v_cndmask_b32_e32 v50, v50, v51, vcc
	v_pk_mul_f32 v[34:35], v[34:35], v[50:51] op_sel_hi:[1,0]
	v_pk_mul_f32 v[48:49], v[48:49], v[50:51] op_sel_hi:[1,0]
	v_pk_mul_f32 v[40:41], v[40:41], v[50:51] op_sel_hi:[1,0]
	v_pk_mul_f32 v[44:45], v[44:45], v[50:51] op_sel_hi:[1,0]
	v_pk_mul_f32 v[42:43], v[42:43], v[50:51] op_sel_hi:[1,0]
	v_pk_mul_f32 v[46:47], v[46:47], v[50:51] op_sel_hi:[1,0]
	v_pk_mul_f32 v[32:33], v[32:33], v[50:51] op_sel_hi:[1,0]
	v_pk_mul_f32 v[36:37], v[36:37], v[50:51] op_sel_hi:[1,0]
	v_mul_f32_e32 v57, 0xbfb8aa3b, v35
	v_mul_f32_e32 v50, 0xbfb8aa3b, v49
	v_mul_f32_e32 v51, 0xbfb8aa3b, v41
	v_mul_f32_e32 v52, 0xbfb8aa3b, v45
	v_mul_f32_e32 v53, 0xbfb8aa3b, v43
	v_mul_f32_e32 v54, 0xbfb8aa3b, v47
	v_mul_f32_e32 v55, 0xbfb8aa3b, v33
	v_mul_f32_e32 v56, 0xbfb8aa3b, v37
	v_exp_f32_e32 v57, v57
	v_exp_f32_e32 v50, v50
	v_exp_f32_e32 v51, v51
	v_exp_f32_e32 v52, v52
	v_exp_f32_e32 v53, v53
	v_exp_f32_e32 v54, v54
	v_exp_f32_e32 v55, v55
	v_exp_f32_e32 v56, v56
	v_add_f32_e32 v57, 1.0, v57
	v_add_f32_e32 v50, 1.0, v50
	v_add_f32_e32 v51, 1.0, v51
	v_add_f32_e32 v52, 1.0, v52
	v_add_f32_e32 v53, 1.0, v53
	v_add_f32_e32 v54, 1.0, v54
	v_add_f32_e32 v55, 1.0, v55
	v_add_f32_e32 v56, 1.0, v56
	v_rcp_f32_e32 v57, v57
	v_rcp_f32_e32 v50, v50
	v_rcp_f32_e32 v51, v51
	v_rcp_f32_e32 v52, v52
	v_rcp_f32_e32 v53, v53
	v_rcp_f32_e32 v54, v54
	v_rcp_f32_e32 v55, v55
	v_rcp_f32_e32 v56, v56
	v_mul_f32_e32 v35, v35, v57
	v_mul_f32_e32 v49, v49, v50
	v_mul_f32_e32 v41, v41, v51
	v_mul_f32_e32 v45, v45, v52
	v_mul_f32_e32 v43, v43, v53
	v_mul_f32_e32 v47, v47, v54
	v_mul_f32_e32 v33, v33, v55
	v_mul_f32_e32 v37, v37, v56
	v_mul_f32_e32 v35, v34, v35
	v_mul_f32_e32 v48, v48, v49
	v_mul_f32_e32 v40, v40, v41
	v_mul_f32_e32 v41, v44, v45
	v_mul_f32_e32 v42, v42, v43
	v_mul_f32_e32 v43, v46, v47
	v_mul_f32_e32 v44, v32, v33
	v_mul_f32_e32 v36, v36, v37
	v_cvt_pk_bf16_f32 v32, v48, v40
	v_cvt_pk_bf16_f32 v33, v41, v42
	v_cvt_pk_bf16_f32 v34, v43, v44
	v_cvt_pk_bf16_f32 v35, v36, v35
	global_store_dwordx4 v[38:39], v[32:35], off nt
	s_nop 0
	s_nop 0
	v_mov_b32_e32 v33, v24
	v_mov_b32_e32 v24, v29
	v_mov_b32_e32 v29, v26
	v_mov_b32_e32 v26, v31
	v_mov_b32_e32 v31, v16
	v_mov_b32_e32 v16, v21
	v_mov_b32_e32 v21, v18
	v_mov_b32_e32 v18, v23
	v_mov_b32_e32 v32, v28
	v_mov_b32_e32 v28, v30
	v_mov_b32_e32 v30, v20
	v_mov_b32_e32 v20, v22
	v_add_u32_e32 v22, 0xa0, v144
	s_waitcnt vmcnt(7)
	v_mov_b32_e32 v34, v252
	v_fmamk_f32 v23, v34, 0x3a800000, v154
	v_mul_f32_e32 v34, 0x4b800000, v23
	v_cmp_gt_f32_e32 vcc, s43, v23
	s_nop 1
	v_cndmask_b32_e32 v23, v23, v34, vcc
	v_rsq_f32_e32 v34, v23
	v_mad_i64_i32 v[22:23], s[0:1], v22, s44, v[120:121]
	v_lshl_add_u64 v[22:23], v[22:23], 0, v[122:123]
	v_mul_f32_e32 v35, 0x45800000, v34
	v_cndmask_b32_e32 v34, v34, v35, vcc
	v_pk_mul_f32 v[18:19], v[18:19], v[34:35] op_sel_hi:[1,0]
	v_pk_mul_f32 v[32:33], v[32:33], v[34:35] op_sel_hi:[1,0]
	v_pk_mul_f32 v[24:25], v[24:25], v[34:35] op_sel_hi:[1,0]
	v_pk_mul_f32 v[28:29], v[28:29], v[34:35] op_sel_hi:[1,0]
	v_pk_mul_f32 v[26:27], v[26:27], v[34:35] op_sel_hi:[1,0]
	v_pk_mul_f32 v[30:31], v[30:31], v[34:35] op_sel_hi:[1,0]
	v_pk_mul_f32 v[16:17], v[16:17], v[34:35] op_sel_hi:[1,0]
	v_pk_mul_f32 v[20:21], v[20:21], v[34:35] op_sel_hi:[1,0]
	v_mul_f32_e32 v41, 0xbfb8aa3b, v19
	v_mul_f32_e32 v34, 0xbfb8aa3b, v33
	v_mul_f32_e32 v35, 0xbfb8aa3b, v25
	v_mul_f32_e32 v36, 0xbfb8aa3b, v29
	v_mul_f32_e32 v37, 0xbfb8aa3b, v27
	v_mul_f32_e32 v38, 0xbfb8aa3b, v31
	v_mul_f32_e32 v39, 0xbfb8aa3b, v17
	v_mul_f32_e32 v40, 0xbfb8aa3b, v21
	v_exp_f32_e32 v41, v41
	v_exp_f32_e32 v34, v34
	v_exp_f32_e32 v35, v35
	v_exp_f32_e32 v36, v36
	v_exp_f32_e32 v37, v37
	v_exp_f32_e32 v38, v38
	v_exp_f32_e32 v39, v39
	v_exp_f32_e32 v40, v40
	v_add_f32_e32 v41, 1.0, v41
	v_add_f32_e32 v34, 1.0, v34
	v_add_f32_e32 v35, 1.0, v35
	v_add_f32_e32 v36, 1.0, v36
	v_add_f32_e32 v37, 1.0, v37
	v_add_f32_e32 v38, 1.0, v38
	v_add_f32_e32 v39, 1.0, v39
	v_add_f32_e32 v40, 1.0, v40
	v_rcp_f32_e32 v41, v41
	v_rcp_f32_e32 v34, v34
	v_rcp_f32_e32 v35, v35
	v_rcp_f32_e32 v36, v36
	v_rcp_f32_e32 v37, v37
	v_rcp_f32_e32 v38, v38
	v_rcp_f32_e32 v39, v39
	v_rcp_f32_e32 v40, v40
	v_mul_f32_e32 v19, v19, v41
	v_mul_f32_e32 v33, v33, v34
	v_mul_f32_e32 v25, v25, v35
	v_mul_f32_e32 v29, v29, v36
	v_mul_f32_e32 v27, v27, v37
	v_mul_f32_e32 v31, v31, v38
	v_mul_f32_e32 v17, v17, v39
	v_mul_f32_e32 v21, v21, v40
	v_mul_f32_e32 v19, v18, v19
	v_mul_f32_e32 v32, v32, v33
	v_mul_f32_e32 v24, v24, v25
	v_mul_f32_e32 v25, v28, v29
	v_mul_f32_e32 v26, v26, v27
	v_mul_f32_e32 v27, v30, v31
	v_mul_f32_e32 v28, v16, v17
	v_mul_f32_e32 v20, v20, v21
	v_cvt_pk_bf16_f32 v16, v32, v24
	v_cvt_pk_bf16_f32 v17, v25, v26
	v_cvt_pk_bf16_f32 v18, v27, v28
	v_cvt_pk_bf16_f32 v19, v20, v19
	global_store_dwordx4 v[22:23], v[16:19], off nt
	s_nop 0
	s_andn2_b64 vcc, exec, s[4:5]
	v_mov_b32_e32 v17, v8
	v_mov_b32_e32 v8, v13
	v_mov_b32_e32 v13, v10
	v_mov_b32_e32 v10, v15
	v_mov_b32_e32 v15, v0
	v_mov_b32_e32 v0, v5
	v_mov_b32_e32 v5, v2
	v_mov_b32_e32 v2, v7
	v_mov_b32_e32 v16, v12
	v_mov_b32_e32 v12, v14
	v_mov_b32_e32 v14, v4
	v_mov_b32_e32 v4, v6
	v_add_u32_e32 v6, 0xb0, v144
	s_waitcnt vmcnt(7)
	v_mov_b32_e32 v18, v253
	v_fmamk_f32 v7, v18, 0x3a800000, v154
	v_mul_f32_e32 v18, 0x4b800000, v7
	v_cmp_gt_f32_e64 s[0:1], s43, v7
	s_nop 1
	v_cndmask_b32_e64 v7, v7, v18, s[0:1]
	v_rsq_f32_e32 v18, v7
	v_mad_i64_i32 v[6:7], s[2:3], v6, s44, v[120:121]
	v_lshl_add_u64 v[6:7], v[6:7], 0, v[122:123]
	v_mul_f32_e32 v19, 0x45800000, v18
	v_cndmask_b32_e64 v18, v18, v19, s[0:1]
	v_pk_mul_f32 v[2:3], v[2:3], v[18:19] op_sel_hi:[1,0]
	v_pk_mul_f32 v[16:17], v[16:17], v[18:19] op_sel_hi:[1,0]
	v_pk_mul_f32 v[8:9], v[8:9], v[18:19] op_sel_hi:[1,0]
	v_pk_mul_f32 v[12:13], v[12:13], v[18:19] op_sel_hi:[1,0]
	v_pk_mul_f32 v[10:11], v[10:11], v[18:19] op_sel_hi:[1,0]
	v_pk_mul_f32 v[14:15], v[14:15], v[18:19] op_sel_hi:[1,0]
	v_pk_mul_f32 v[0:1], v[0:1], v[18:19] op_sel_hi:[1,0]
	v_pk_mul_f32 v[4:5], v[4:5], v[18:19] op_sel_hi:[1,0]
	v_mul_f32_e32 v25, 0xbfb8aa3b, v3
	v_mul_f32_e32 v18, 0xbfb8aa3b, v17
	v_mul_f32_e32 v19, 0xbfb8aa3b, v9
	v_mul_f32_e32 v20, 0xbfb8aa3b, v13
	v_mul_f32_e32 v21, 0xbfb8aa3b, v11
	v_mul_f32_e32 v22, 0xbfb8aa3b, v15
	v_mul_f32_e32 v23, 0xbfb8aa3b, v1
	v_mul_f32_e32 v24, 0xbfb8aa3b, v5
	v_exp_f32_e32 v25, v25
	v_exp_f32_e32 v18, v18
	v_exp_f32_e32 v19, v19
	v_exp_f32_e32 v20, v20
	v_exp_f32_e32 v21, v21
	v_exp_f32_e32 v22, v22
	v_exp_f32_e32 v23, v23
	v_exp_f32_e32 v24, v24
	v_add_f32_e32 v25, 1.0, v25
	v_add_f32_e32 v18, 1.0, v18
	v_add_f32_e32 v19, 1.0, v19
	v_add_f32_e32 v20, 1.0, v20
	v_add_f32_e32 v21, 1.0, v21
	v_add_f32_e32 v22, 1.0, v22
	v_add_f32_e32 v23, 1.0, v23
	v_add_f32_e32 v24, 1.0, v24
	v_rcp_f32_e32 v25, v25
	v_rcp_f32_e32 v18, v18
	v_rcp_f32_e32 v19, v19
	v_rcp_f32_e32 v20, v20
	v_rcp_f32_e32 v21, v21
	v_rcp_f32_e32 v22, v22
	v_rcp_f32_e32 v23, v23
	v_rcp_f32_e32 v24, v24
	v_mul_f32_e32 v3, v3, v25
	v_mul_f32_e32 v17, v17, v18
	v_mul_f32_e32 v9, v9, v19
	v_mul_f32_e32 v13, v13, v20
	v_mul_f32_e32 v11, v11, v21
	v_mul_f32_e32 v15, v15, v22
	v_mul_f32_e32 v1, v1, v23
	v_mul_f32_e32 v5, v5, v24
	v_mul_f32_e32 v3, v2, v3
	s_mov_b64 s[0:1], -1
	v_mul_f32_e32 v16, v16, v17
	v_mul_f32_e32 v8, v8, v9
	v_mul_f32_e32 v9, v12, v13
	v_mul_f32_e32 v10, v10, v11
	v_mul_f32_e32 v11, v14, v15
	v_mul_f32_e32 v12, v0, v1
	v_mul_f32_e32 v4, v4, v5
	v_cvt_pk_bf16_f32 v0, v16, v8
	v_cvt_pk_bf16_f32 v1, v9, v10
	v_cvt_pk_bf16_f32 v2, v11, v12
	v_cvt_pk_bf16_f32 v3, v4, v3
	global_store_dwordx4 v[6:7], v[0:3], off nt
	s_cbranch_vccnz .LBB0_1045
	s_andn2_b64 vcc, exec, s[8:9]
	s_cbranch_vccnz .LBB0_1044
	s_barrier
	s_branch .LBB0_1044
